# phase-0 GEMV switched to rolling prefetch: next trip's weight-row load i issued right after load i is consumed (last trip re-loads own rows), constant vmcnt(15) waits
# baseline (speedup 1.0000x reference)
; #define LAS __attribute__((address_space(3)))
; __device__ __forceinline__ void phase0(CArgs a, LAS unsigned char* lds, int tid, int lane, int wave, int G, int bx) {
;     ...
;             for (int kk = 0; kk < 128; kk += 16) {
;                 const int k = kb + kk; const float* wp = Wl + (size_t)(half * 1024 + k) * NMOD;
;                 f32x2 wv[16];
; #pragma unroll
;                 for (int i = 0; i < 16; ++i) wv[i] = __builtin_nontemporal_load((const f32x2*)(wp + (size_t)i * NMOD));
; #pragma unroll
;                 for (int q = 0; q < 4; ++q) {
; #pragma unroll
;                     for (int r = 0; r < NB; ++r) { const f32x4 s4 = *(const LAS f32x4*)(S + r * 1024 + k + 4 * q);
;                         acc[r] += wv[4 * q] * s4[0]; acc[r] += wv[4 * q + 1] * s4[1]; acc[r] += wv[4 * q + 2] * s4[2]; acc[r] += wv[4 * q + 3] * s4[3]; } }
.LBB0_842:
	s_or_b64 exec, exec, s[4:5]
	s_add_i32 s2, s10, s14
	v_mov_b32_e32 v12, 0xc000
	v_mad_i64_i32 v[12:13], s[2:3], s2, v12, v[10:11]
	s_xor_b64 s[4:5], s[6:7], -1
	s_mov_b32 s2, -16
	s_mov_b32 s3, s11
	s_waitcnt lgkmcnt(0)
	s_barrier
	s_mov_b32 s45, -1
	s_mov_b32 s44, 0xfff4c000
	v_lshl_add_u64 v[206:207], v[12:13], 0, s[44:45]
	global_load_dwordx2 v[220:221], v[206:207], off nt
	s_mov_b32 s44, 0xfff58000
	v_lshl_add_u64 v[206:207], v[12:13], 0, s[44:45]
	global_load_dwordx2 v[222:223], v[206:207], off nt
	s_mov_b32 s44, 0xfff64000
	v_lshl_add_u64 v[206:207], v[12:13], 0, s[44:45]
	global_load_dwordx2 v[224:225], v[206:207], off nt
	s_mov_b32 s44, 0xfff70000
	v_lshl_add_u64 v[206:207], v[12:13], 0, s[44:45]
	global_load_dwordx2 v[226:227], v[206:207], off nt
	s_mov_b32 s44, 0xfff7c000
	v_lshl_add_u64 v[206:207], v[12:13], 0, s[44:45]
	global_load_dwordx2 v[228:229], v[206:207], off nt
	s_mov_b32 s44, 0xfff88000
	v_lshl_add_u64 v[206:207], v[12:13], 0, s[44:45]
	global_load_dwordx2 v[230:231], v[206:207], off nt
	s_mov_b32 s44, 0xfff94000
	v_lshl_add_u64 v[206:207], v[12:13], 0, s[44:45]
	global_load_dwordx2 v[232:233], v[206:207], off nt
	s_mov_b32 s44, 0xfffa0000
	v_lshl_add_u64 v[206:207], v[12:13], 0, s[44:45]
	global_load_dwordx2 v[234:235], v[206:207], off nt
	s_mov_b32 s44, 0xfffac000
	v_lshl_add_u64 v[206:207], v[12:13], 0, s[44:45]
	global_load_dwordx2 v[236:237], v[206:207], off nt
	s_mov_b32 s44, 0xfffb8000
	v_lshl_add_u64 v[206:207], v[12:13], 0, s[44:45]
	global_load_dwordx2 v[238:239], v[206:207], off nt
	s_mov_b32 s44, 0xfffc4000
	v_lshl_add_u64 v[206:207], v[12:13], 0, s[44:45]
	global_load_dwordx2 v[240:241], v[206:207], off nt
	s_mov_b32 s44, 0xfffd0000
	v_lshl_add_u64 v[206:207], v[12:13], 0, s[44:45]
	global_load_dwordx2 v[242:243], v[206:207], off nt
	s_mov_b32 s44, 0xfffdc000
	v_lshl_add_u64 v[206:207], v[12:13], 0, s[44:45]
	global_load_dwordx2 v[244:245], v[206:207], off nt
	s_mov_b32 s44, 0xfffe8000
	v_lshl_add_u64 v[206:207], v[12:13], 0, s[44:45]
	global_load_dwordx2 v[246:247], v[206:207], off nt
	s_mov_b32 s44, 0xffff4000
	v_lshl_add_u64 v[206:207], v[12:13], 0, s[44:45]
	global_load_dwordx2 v[248:249], v[206:207], off nt
	global_load_dwordx2 v[250:251], v[12:13], off nt
.LBB0_843:
	s_cmp_eq_u32 s2, 0x60
	s_cselect_b32 s48, 0, 0xc0000
	s_mov_b32 s49, 0
	v_lshl_add_u64 v[208:209], v[12:13], 0, s[48:49]
	s_mov_b32 s6, 0xfff4c000
	v_add_co_u32_e32 v34, vcc, s6, v12
	s_mov_b32 s6, 0xfff58000
	s_nop 0
	v_addc_co_u32_e32 v35, vcc, -1, v13, vcc
	v_add_co_u32_e32 v42, vcc, s6, v12
	s_mov_b32 s6, 0xfff64000
	s_nop 0
	v_addc_co_u32_e32 v43, vcc, -1, v13, vcc
	v_add_co_u32_e32 v44, vcc, s6, v12
	s_mov_b32 s6, 0xfff70000
	s_nop 0
	v_addc_co_u32_e32 v45, vcc, -1, v13, vcc
	v_add_co_u32_e32 v46, vcc, s6, v12
	s_add_i32 s6, s3, 0xfffdefd0
	s_nop 0
	v_addc_co_u32_e32 v47, vcc, -1, v13, vcc
	s_nop 0
	s_add_i32 s7, s3, 0xfffdffd0
	s_add_i32 s8, s3, 0xfffe0fd0
	s_add_i32 s9, s3, 0xfffe1fd0
	s_add_i32 s14, s3, 0xfffe2fd0
	s_add_i32 s15, s3, 0xfffe3fd0
	s_add_i32 s16, s3, 0xfffe4fd0
	s_add_i32 s17, s3, 0xfffe5fd0
	v_mov_b32_e32 v42, s6
	v_mov_b32_e32 v46, s7
	v_mov_b32_e32 v50, s8
	v_mov_b32_e32 v54, s9
	v_mov_b32_e32 v58, s14
	v_mov_b32_e32 v62, s15
	v_mov_b32_e32 v66, s16
	v_mov_b32_e32 v70, s17
	ds_read_b128 v[42:45], v42
	ds_read_b128 v[46:49], v46
	ds_read_b128 v[50:53], v50
	ds_read_b128 v[54:57], v54
	ds_read_b128 v[58:61], v58
	ds_read_b128 v[62:65], v62
	ds_read_b128 v[66:69], v66
	ds_read_b128 v[70:73], v70
	s_add_i32 s18, s3, 0xfffe6fd0
	v_mov_b32_e32 v97, s18
	s_add_i32 s19, s3, 0xfffe7fd0
	s_waitcnt lgkmcnt(7)
	v_mov_b32_e32 v98, v45
	v_mov_b32_e32 v99, s19
	s_add_i32 s20, s3, 0xfffe8fd0
	s_waitcnt lgkmcnt(6)
	v_mov_b32_e32 v96, v49
	v_mov_b32_e32 v103, s20
	s_add_i32 s21, s3, 0xfffe9fd0
	s_waitcnt lgkmcnt(5)
	v_mov_b32_e32 v102, v53
	v_mov_b32_e32 v104, s21
	s_add_i32 s22, s3, 0xfffeafd0
	s_waitcnt lgkmcnt(4)
	v_mov_b32_e32 v112, v57
	s_add_i32 s23, s3, 0xfffebfd0
	v_mov_b32_e32 v105, s22
	v_mov_b32_e32 v106, s23
	s_waitcnt lgkmcnt(3)
	v_mov_b32_e32 v110, v61
	s_waitcnt lgkmcnt(2)
	v_mov_b32_e32 v118, v65
	s_add_i32 s24, s3, 0xfffecfd0
	v_mov_b32_e32 v107, s24
	s_add_i32 s25, s3, 0xfffedfd0
	s_add_i32 s26, s3, 0xfffeefd0
	s_add_i32 s27, s3, 0xfffeffd0
	v_mov_b32_e32 v111, s25
	v_mov_b32_e32 v113, s26
	v_mov_b32_e32 v119, s27
	s_waitcnt lgkmcnt(1)
	v_mov_b32_e32 v124, v69
	s_waitcnt lgkmcnt(0)
	v_mov_b32_e32 v122, v73
	s_add_i32 s28, s3, 0xffff0fd0
	s_add_i32 s29, s3, 0xffff1fd0
	v_mov_b32_e32 v123, s28
	v_mov_b32_e32 v125, s29
	s_add_i32 s30, s3, 0xffff2fd0
	s_add_i32 s31, s3, 0xffff3fd0
	v_mov_b32_e32 v131, s30
	v_mov_b32_e32 v154, s31
	s_add_i32 s6, s3, 0xffff4fd0
	s_add_i32 s7, s3, 0xffff5fd0
	s_add_i32 s8, s3, 0xfffe0fe0
	s_add_i32 s9, s3, 0xfffe1fe0
	s_add_i32 s31, s3, 0xffff3fe0
	s_add_i32 s14, s3, 0xfffe2fe0
	s_add_i32 s15, s3, 0xfffe3fe0
	s_add_i32 s16, s3, 0xfffe4fe0
	s_add_i32 s17, s3, 0xfffe5fe0
	s_add_i32 s18, s3, 0xfffe6fe0
	s_add_i32 s19, s3, 0xfffe7fe0
	s_add_i32 s20, s3, 0xfffe8fe0
	s_add_i32 s21, s3, 0xfffe9fe0
	s_add_i32 s22, s3, 0xfffeafe0
	s_add_i32 s23, s3, 0xfffebfe0
	s_add_i32 s24, s3, 0xfffecfe0
	s_add_i32 s25, s3, 0xfffedfe0
	s_add_i32 s26, s3, 0xfffeefe0
	s_add_i32 s27, s3, 0xfffeffe0
	s_add_i32 s28, s3, 0xffff0fe0
	s_add_i32 s29, s3, 0xffff1fe0
	s_add_i32 s30, s3, 0xffff2fe0
	s_add_i32 s33, s3, 0xffff5000
	s_add_i32 s34, s3, 0xffff6000
	s_waitcnt vmcnt(15)
	v_mov_b32_e32 v90, v220
	v_mov_b32_e32 v91, v221
	s_mov_b32 s44, 0xfff4c000
	v_lshl_add_u64 v[206:207], v[208:209], 0, s[44:45]
	global_load_dwordx2 v[220:221], v[206:207], off nt
	v_pk_fma_f32 v[88:89], v[90:91], v[42:43], v[88:89] op_sel_hi:[1,0,1]
	s_add_i32 s2, s2, 16
	s_waitcnt vmcnt(15)
; #define LAS __attribute__((address_space(3)))
; __device__ __forceinline__ void phase0(CArgs a, LAS unsigned char* lds, int tid, int lane, int wave, int G, int bx) {
;     ...
;                 for (int i = 0; i < 16; ++i) wv[i] = __builtin_nontemporal_load((const f32x2*)(wp + (size_t)i * NMOD));
; #pragma unroll
;                 for (int q = 0; q < 4; ++q) {
; #pragma unroll
;                     for (int r = 0; r < NB; ++r) { const f32x4 s4 = *(const LAS f32x4*)(S + r * 1024 + k + 4 * q);
;                         acc[r] += wv[4 * q] * s4[0]; acc[r] += wv[4 * q + 1] * s4[1]; acc[r] += wv[4 * q + 2] * s4[2]; acc[r] += wv[4 * q + 3] * s4[3]; } }
	v_mov_b32_e32 v92, v222
	v_mov_b32_e32 v93, v223
	s_mov_b32 s44, 0xfff58000
	v_lshl_add_u64 v[206:207], v[208:209], 0, s[44:45]
	global_load_dwordx2 v[222:223], v[206:207], off nt
	v_pk_fma_f32 v[42:43], v[92:93], v[42:43], v[88:89] op_sel:[0,1,0]
	s_waitcnt vmcnt(15)
	v_mov_b32_e32 v94, v224
	v_mov_b32_e32 v95, v225
	s_mov_b32 s44, 0xfff64000
	v_lshl_add_u64 v[206:207], v[208:209], 0, s[44:45]
	global_load_dwordx2 v[224:225], v[206:207], off nt
	v_pk_fma_f32 v[88:89], v[94:95], v[44:45], v[42:43] op_sel_hi:[1,0,1]
	v_pk_fma_f32 v[42:43], v[90:91], v[46:47], v[86:87] op_sel_hi:[1,0,1]
	s_waitcnt vmcnt(15)
	v_mov_b32_e32 v34, v226
	v_mov_b32_e32 v35, v227
	s_mov_b32 s44, 0xfff70000
	v_lshl_add_u64 v[206:207], v[208:209], 0, s[44:45]
	global_load_dwordx2 v[226:227], v[206:207], off nt
	v_pk_fma_f32 v[156:157], v[34:35], v[98:99], v[88:89] op_sel_hi:[1,0,1]
	v_pk_fma_f32 v[42:43], v[92:93], v[46:47], v[42:43] op_sel:[0,1,0]
	v_pk_fma_f32 v[46:47], v[90:91], v[50:51], v[84:85] op_sel_hi:[1,0,1]
	v_pk_fma_f32 v[86:87], v[94:95], v[48:49], v[42:43] op_sel_hi:[1,0,1]
	ds_read_b128 v[42:45], v97
	v_pk_fma_f32 v[46:47], v[92:93], v[50:51], v[46:47] op_sel:[0,1,0]
	v_pk_fma_f32 v[50:51], v[90:91], v[54:55], v[82:83] op_sel_hi:[1,0,1]
	v_pk_fma_f32 v[100:101], v[94:95], v[52:53], v[46:47] op_sel_hi:[1,0,1]
	v_pk_fma_f32 v[50:51], v[92:93], v[54:55], v[50:51] op_sel:[0,1,0]
	ds_read_b128 v[46:49], v99
	v_pk_fma_f32 v[108:109], v[94:95], v[56:57], v[50:51] op_sel_hi:[1,0,1]
	v_pk_fma_f32 v[50:51], v[90:91], v[58:59], v[80:81] op_sel_hi:[1,0,1]
	v_pk_fma_f32 v[54:55], v[90:91], v[62:63], v[78:79] op_sel_hi:[1,0,1]
	v_pk_fma_f32 v[50:51], v[92:93], v[58:59], v[50:51] op_sel:[0,1,0]
	v_pk_fma_f32 v[58:59], v[90:91], v[66:67], v[76:77] op_sel_hi:[1,0,1]
	v_pk_fma_f32 v[114:115], v[94:95], v[60:61], v[50:51] op_sel_hi:[1,0,1]
	ds_read_b128 v[50:53], v103
	v_pk_fma_f32 v[54:55], v[92:93], v[62:63], v[54:55] op_sel:[0,1,0]
	v_pk_fma_f32 v[58:59], v[92:93], v[66:67], v[58:59] op_sel:[0,1,0]
	s_waitcnt lgkmcnt(2)
	v_pk_fma_f32 v[62:63], v[90:91], v[42:43], v[152:153] op_sel_hi:[1,0,1]
	v_pk_fma_f32 v[116:117], v[94:95], v[64:65], v[54:55] op_sel_hi:[1,0,1]
	ds_read_b128 v[54:57], v104
	v_pk_fma_f32 v[120:121], v[94:95], v[68:69], v[58:59] op_sel_hi:[1,0,1]
	v_pk_fma_f32 v[58:59], v[90:91], v[70:71], v[74:75] op_sel_hi:[1,0,1]
	v_pk_fma_f32 v[42:43], v[92:93], v[42:43], v[62:63] op_sel:[0,1,0]
	v_pk_fma_f32 v[58:59], v[92:93], v[70:71], v[58:59] op_sel:[0,1,0]
	v_pk_fma_f32 v[128:129], v[94:95], v[44:45], v[42:43] op_sel_hi:[1,0,1]
	s_waitcnt lgkmcnt(2)
	v_pk_fma_f32 v[42:43], v[90:91], v[46:47], v[150:151] op_sel_hi:[1,0,1]
	v_pk_fma_f32 v[126:127], v[94:95], v[72:73], v[58:59] op_sel_hi:[1,0,1]
	ds_read_b128 v[58:61], v105
	ds_read_b128 v[62:65], v106
	v_pk_fma_f32 v[42:43], v[92:93], v[46:47], v[42:43] op_sel:[0,1,0]
	s_waitcnt lgkmcnt(3)
	v_mov_b32_e32 v82, v53
	v_pk_fma_f32 v[104:105], v[94:95], v[48:49], v[42:43] op_sel_hi:[1,0,1]
	v_pk_fma_f32 v[42:43], v[90:91], v[50:51], v[148:149] op_sel_hi:[1,0,1]
	v_mov_b32_e32 v106, v49
	v_pk_fma_f32 v[42:43], v[92:93], v[50:51], v[42:43] op_sel:[0,1,0]
	s_waitcnt lgkmcnt(0)
	v_pk_fma_f32 v[48:49], v[90:91], v[62:63], v[142:143] op_sel_hi:[1,0,1]
	v_pk_fma_f32 v[84:85], v[94:95], v[52:53], v[42:43] op_sel_hi:[1,0,1]
	v_pk_fma_f32 v[42:43], v[90:91], v[54:55], v[146:147] op_sel_hi:[1,0,1]
	ds_read_b128 v[50:53], v107
	ds_read_b128 v[66:69], v111
	v_pk_fma_f32 v[42:43], v[92:93], v[54:55], v[42:43] op_sel:[0,1,0]
	v_mov_b32_e32 v130, v45
	v_pk_fma_f32 v[78:79], v[94:95], v[56:57], v[42:43] op_sel_hi:[1,0,1]
	v_pk_fma_f32 v[42:43], v[90:91], v[58:59], v[144:145] op_sel_hi:[1,0,1]
	v_mov_b32_e32 v46, v61
	v_pk_fma_f32 v[42:43], v[92:93], v[58:59], v[42:43] op_sel:[0,1,0]
	v_pk_fma_f32 v[48:49], v[92:93], v[62:63], v[48:49] op_sel:[0,1,0]
	v_pk_fma_f32 v[44:45], v[94:95], v[60:61], v[42:43] op_sel_hi:[1,0,1]
	ds_read_b128 v[60:63], v113
	ds_read_b128 v[70:73], v119
	s_waitcnt lgkmcnt(3)
	v_pk_fma_f32 v[54:55], v[90:91], v[50:51], v[140:141] op_sel_hi:[1,0,1]
	v_mov_b32_e32 v80, v57
	v_pk_fma_f32 v[50:51], v[92:93], v[50:51], v[54:55] op_sel:[0,1,0]
	v_mov_b32_e32 v54, v53
	v_pk_fma_f32 v[50:51], v[94:95], v[52:53], v[50:51] op_sel_hi:[1,0,1]
	s_waitcnt lgkmcnt(2)
	v_pk_fma_f32 v[52:53], v[90:91], v[66:67], v[134:135] op_sel_hi:[1,0,1]
	s_waitcnt lgkmcnt(1)
	v_pk_fma_f32 v[2:3], v[90:91], v[60:61], v[2:3] op_sel_hi:[1,0,1]
	s_waitcnt lgkmcnt(0)
	v_pk_fma_f32 v[0:1], v[90:91], v[70:71], v[0:1] op_sel_hi:[1,0,1]
	v_pk_fma_f32 v[52:53], v[92:93], v[66:67], v[52:53] op_sel:[0,1,0]
	v_pk_fma_f32 v[2:3], v[92:93], v[60:61], v[2:3] op_sel:[0,1,0]
	v_pk_fma_f32 v[0:1], v[92:93], v[70:71], v[0:1] op_sel:[0,1,0]
	v_pk_fma_f32 v[56:57], v[94:95], v[68:69], v[52:53] op_sel_hi:[1,0,1]
	v_mov_b32_e32 v52, v63
	v_pk_fma_f32 v[60:61], v[94:95], v[62:63], v[2:3] op_sel_hi:[1,0,1]
	ds_read_b128 v[74:77], v123
	v_pk_fma_f32 v[62:63], v[94:95], v[72:73], v[0:1] op_sel_hi:[1,0,1]
	ds_read_b128 v[0:3], v125
	v_mov_b32_e32 v42, v65
	v_pk_fma_f32 v[48:49], v[94:95], v[64:65], v[48:49] op_sel_hi:[1,0,1]
	v_mov_b32_e32 v66, v73
	s_waitcnt lgkmcnt(1)
	v_pk_fma_f32 v[64:65], v[90:91], v[74:75], v[138:139] op_sel_hi:[1,0,1]
	s_waitcnt lgkmcnt(0)
	v_pk_fma_f32 v[72:73], v[90:91], v[0:1], v[136:137] op_sel_hi:[1,0,1]
	v_pk_fma_f32 v[64:65], v[92:93], v[74:75], v[64:65] op_sel:[0,1,0]
	v_pk_fma_f32 v[0:1], v[92:93], v[0:1], v[72:73] op_sel:[0,1,0]
	v_mov_b32_e32 v58, v69
	v_pk_fma_f32 v[68:69], v[94:95], v[76:77], v[64:65] op_sel_hi:[1,0,1]
	v_mov_b32_e32 v70, v77
	v_mov_b32_e32 v64, v3
	v_pk_fma_f32 v[72:73], v[94:95], v[2:3], v[0:1] op_sel_hi:[1,0,1]
	ds_read_b128 v[74:77], v131
	ds_read_b128 v[0:3], v154
	v_pk_fma_f32 v[174:175], v[34:35], v[42:43], v[48:49] op_sel_hi:[1,0,1]
	v_mov_b32_e32 v42, s8
	v_pk_fma_f32 v[98:99], v[34:35], v[124:125], v[120:121] op_sel_hi:[1,0,1]
	s_waitcnt lgkmcnt(1)
; #define LAS __attribute__((address_space(3)))
; __device__ __forceinline__ void phase0(CArgs a, LAS unsigned char* lds, int tid, int lane, int wave, int G, int bx) {
;     ...
;                 for (int i = 0; i < 16; ++i) wv[i] = __builtin_nontemporal_load((const f32x2*)(wp + (size_t)i * NMOD));
; #pragma unroll
;                 for (int q = 0; q < 4; ++q) {
; #pragma unroll
;                     for (int r = 0; r < NB; ++r) { const f32x4 s4 = *(const LAS f32x4*)(S + r * 1024 + k + 4 * q);
;                         acc[r] += wv[4 * q] * s4[0]; acc[r] += wv[4 * q + 1] * s4[1]; acc[r] += wv[4 * q + 2] * s4[2]; acc[r] += wv[4 * q + 3] * s4[3]; } }
	v_pk_fma_f32 v[132:133], v[90:91], v[74:75], v[132:133] op_sel_hi:[1,0,1]
	s_waitcnt lgkmcnt(0)
	v_pk_fma_f32 v[40:41], v[90:91], v[0:1], v[40:41] op_sel_hi:[1,0,1]
	v_pk_fma_f32 v[74:75], v[92:93], v[74:75], v[132:133] op_sel:[0,1,0]
	v_pk_fma_f32 v[0:1], v[92:93], v[0:1], v[40:41] op_sel:[0,1,0]
	v_mov_b32_e32 v40, s7
	v_pk_fma_f32 v[0:1], v[94:95], v[2:3], v[0:1] op_sel_hi:[1,0,1]
	v_mov_b32_e32 v2, v3
	v_mov_b32_e32 v3, s6
	ds_read_b128 v[132:135], v3
	ds_read_b128 v[136:139], v40
	s_add_i32 s6, s3, 0xffff6fd0
	s_add_i32 s7, s3, 0xffff7fd0
	v_mov_b32_e32 v3, s6
	s_waitcnt lgkmcnt(1)
	v_pk_fma_f32 v[38:39], v[90:91], v[132:133], v[38:39] op_sel_hi:[1,0,1]
	s_waitcnt lgkmcnt(0)
	v_pk_fma_f32 v[36:37], v[90:91], v[136:137], v[36:37] op_sel_hi:[1,0,1]
	v_pk_fma_f32 v[38:39], v[92:93], v[132:133], v[38:39] op_sel:[0,1,0]
	v_pk_fma_f32 v[36:37], v[92:93], v[136:137], v[36:37] op_sel:[0,1,0]
	v_pk_fma_f32 v[38:39], v[94:95], v[134:135], v[38:39] op_sel_hi:[1,0,1]
	v_mov_b32_e32 v40, v135
	v_pk_fma_f32 v[36:37], v[94:95], v[138:139], v[36:37] op_sel_hi:[1,0,1]
	v_mov_b32_e32 v132, v139
	v_mov_b32_e32 v41, s7
	ds_read_b128 v[134:137], v3
	ds_read_b128 v[138:141], v41
	s_add_i32 s6, s3, 0xffff8fd0
	s_add_i32 s7, s3, 0xffff9fd0
	v_mov_b32_e32 v3, s6
	s_waitcnt lgkmcnt(1)
	v_pk_fma_f32 v[32:33], v[90:91], v[134:135], v[32:33] op_sel_hi:[1,0,1]
	s_waitcnt lgkmcnt(0)
	v_pk_fma_f32 v[30:31], v[90:91], v[138:139], v[30:31] op_sel_hi:[1,0,1]
	v_pk_fma_f32 v[32:33], v[92:93], v[134:135], v[32:33] op_sel:[0,1,0]
	v_pk_fma_f32 v[30:31], v[92:93], v[138:139], v[30:31] op_sel:[0,1,0]
	v_pk_fma_f32 v[32:33], v[94:95], v[136:137], v[32:33] op_sel_hi:[1,0,1]
	v_pk_fma_f32 v[30:31], v[94:95], v[140:141], v[30:31] op_sel_hi:[1,0,1]
	v_mov_b32_e32 v136, v141
	v_mov_b32_e32 v41, s7
	ds_read_b128 v[138:141], v3
	ds_read_b128 v[142:145], v41
	s_add_i32 s6, s3, 0xffffafd0
	s_add_i32 s7, s3, 0xffffbfd0
	v_mov_b32_e32 v3, s6
	s_waitcnt lgkmcnt(1)
	v_pk_fma_f32 v[28:29], v[90:91], v[138:139], v[28:29] op_sel_hi:[1,0,1]
	s_waitcnt lgkmcnt(0)
	v_pk_fma_f32 v[26:27], v[90:91], v[142:143], v[26:27] op_sel_hi:[1,0,1]
	v_pk_fma_f32 v[28:29], v[92:93], v[138:139], v[28:29] op_sel:[0,1,0]
	v_pk_fma_f32 v[26:27], v[92:93], v[142:143], v[26:27] op_sel:[0,1,0]
	v_pk_fma_f32 v[28:29], v[94:95], v[140:141], v[28:29] op_sel_hi:[1,0,1]
	v_pk_fma_f32 v[26:27], v[94:95], v[144:145], v[26:27] op_sel_hi:[1,0,1]
	v_mov_b32_e32 v140, v145
	v_mov_b32_e32 v41, s7
	ds_read_b128 v[142:145], v3
	ds_read_b128 v[146:149], v41
	s_add_i32 s6, s3, 0xffffcfd0
	s_add_i32 s7, s3, 0xffffdfd0
	v_mov_b32_e32 v3, s6
	s_waitcnt lgkmcnt(1)
	v_pk_fma_f32 v[24:25], v[90:91], v[142:143], v[24:25] op_sel_hi:[1,0,1]
	s_waitcnt lgkmcnt(0)
	v_pk_fma_f32 v[22:23], v[90:91], v[146:147], v[22:23] op_sel_hi:[1,0,1]
	v_pk_fma_f32 v[24:25], v[92:93], v[142:143], v[24:25] op_sel:[0,1,0]
	v_pk_fma_f32 v[22:23], v[92:93], v[146:147], v[22:23] op_sel:[0,1,0]
	v_pk_fma_f32 v[24:25], v[94:95], v[144:145], v[24:25] op_sel_hi:[1,0,1]
	v_pk_fma_f32 v[22:23], v[94:95], v[148:149], v[22:23] op_sel_hi:[1,0,1]
	v_mov_b32_e32 v144, v149
	v_mov_b32_e32 v41, s7
	ds_read_b128 v[146:149], v3
	ds_read_b128 v[150:153], v41
	s_add_i32 s6, s3, 0xffffefd0
	s_sub_i32 s7, s3, 48
	v_mov_b32_e32 v3, s6
	s_waitcnt lgkmcnt(1)
	v_pk_fma_f32 v[20:21], v[90:91], v[146:147], v[20:21] op_sel_hi:[1,0,1]
	s_waitcnt lgkmcnt(0)
	v_pk_fma_f32 v[18:19], v[90:91], v[150:151], v[18:19] op_sel_hi:[1,0,1]
	v_pk_fma_f32 v[20:21], v[92:93], v[146:147], v[20:21] op_sel:[0,1,0]
	v_pk_fma_f32 v[18:19], v[92:93], v[150:151], v[18:19] op_sel:[0,1,0]
	v_pk_fma_f32 v[20:21], v[94:95], v[148:149], v[20:21] op_sel_hi:[1,0,1]
	v_pk_fma_f32 v[18:19], v[94:95], v[152:153], v[18:19] op_sel_hi:[1,0,1]
	v_mov_b32_e32 v148, v153
	v_mov_b32_e32 v41, s7
	ds_read_b128 v[152:155], v3
	ds_read_b128 v[168:171], v41
	s_mov_b32 s6, 0xfff7c000
	v_mov_b32_e32 v138, v141
	s_add_i32 s7, s3, 0xfffdffe0
	s_waitcnt lgkmcnt(1)
	v_pk_fma_f32 v[16:17], v[90:91], v[152:153], v[16:17] op_sel_hi:[1,0,1]
	s_waitcnt lgkmcnt(0)
	v_pk_fma_f32 v[14:15], v[90:91], v[168:169], v[14:15] op_sel_hi:[1,0,1]
	v_pk_fma_f32 v[90:91], v[34:35], v[96:97], v[86:87] op_sel_hi:[1,0,1]
	v_pk_fma_f32 v[14:15], v[92:93], v[168:169], v[14:15] op_sel:[0,1,0]
	v_pk_fma_f32 v[168:169], v[34:35], v[82:83], v[84:85] op_sel_hi:[1,0,1]
	v_pk_fma_f32 v[158:159], v[94:95], v[170:171], v[14:15] op_sel_hi:[1,0,1]
	v_add_co_u32_e32 v14, vcc, s6, v12
	s_mov_b32 s6, 0xfff88000
	s_nop 0
	v_addc_co_u32_e32 v15, vcc, -1, v13, vcc
	v_add_co_u32_e32 v96, vcc, s6, v12
	s_mov_b32 s6, 0xfff94000
	s_nop 0
	v_addc_co_u32_e32 v97, vcc, -1, v13, vcc
	v_add_co_u32_e32 v82, vcc, s6, v12
	s_mov_b32 s6, 0xfffa0000
	s_nop 0
	v_addc_co_u32_e32 v83, vcc, -1, v13, vcc
	v_add_co_u32_e32 v84, vcc, s6, v12
	v_mov_b32_e32 v160, v171
	v_pk_fma_f32 v[170:171], v[34:35], v[80:81], v[78:79] op_sel_hi:[1,0,1]
	v_addc_co_u32_e32 v85, vcc, -1, v13, vcc
	s_nop 0
	s_nop 0
	s_add_i32 s6, s3, 0xfffdefe0
	v_pk_fma_f32 v[16:17], v[92:93], v[152:153], v[16:17] op_sel:[0,1,0]
	v_mov_b32_e32 v3, s6
	v_pk_fma_f32 v[152:153], v[94:95], v[154:155], v[16:17] op_sel_hi:[1,0,1]
	v_pk_fma_f32 v[16:17], v[34:35], v[130:131], v[128:129] op_sel_hi:[1,0,1]
	v_pk_fma_f32 v[130:131], v[34:35], v[2:3], v[0:1] op_sel_hi:[1,0,1]
	ds_read_b128 v[0:3], v3
	v_pk_fma_f32 v[74:75], v[94:95], v[76:77], v[74:75] op_sel_hi:[1,0,1]
	v_mov_b32_e32 v134, v137
	v_pk_fma_f32 v[94:95], v[34:35], v[118:119], v[116:117] op_sel_hi:[1,0,1]
	v_mov_b32_e32 v41, s7
	v_pk_fma_f32 v[120:121], v[34:35], v[138:139], v[28:29] op_sel_hi:[1,0,1]
	v_pk_fma_f32 v[118:119], v[34:35], v[140:141], v[26:27] op_sel_hi:[1,0,1]
; #define LAS __attribute__((address_space(3)))
; __device__ __forceinline__ void phase0(CArgs a, LAS unsigned char* lds, int tid, int lane, int wave, int G, int bx) {
;     ...
;                 for (int i = 0; i < 16; ++i) wv[i] = __builtin_nontemporal_load((const f32x2*)(wp + (size_t)i * NMOD));
; #pragma unroll
;                 for (int q = 0; q < 4; ++q) {
; #pragma unroll
;                     for (int r = 0; r < NB; ++r) { const f32x4 s4 = *(const LAS f32x4*)(S + r * 1024 + k + 4 * q);
;                         acc[r] += wv[4 * q] * s4[0]; acc[r] += wv[4 * q + 1] * s4[1]; acc[r] += wv[4 * q + 2] * s4[2]; acc[r] += wv[4 * q + 3] * s4[3]; } }
	ds_read_b128 v[26:29], v42
	v_pk_fma_f32 v[86:87], v[34:35], v[112:113], v[108:109] op_sel_hi:[1,0,1]
	v_pk_fma_f32 v[108:109], v[34:35], v[122:123], v[126:127] op_sel_hi:[1,0,1]
	v_mov_b32_e32 v43, s9
	v_mov_b32_e32 v133, s31
	v_pk_fma_f32 v[124:125], v[34:35], v[134:135], v[32:33] op_sel_hi:[1,0,1]
	v_pk_fma_f32 v[122:123], v[34:35], v[136:137], v[30:31] op_sel_hi:[1,0,1]
	ds_read_b128 v[30:33], v41
	v_pk_fma_f32 v[128:129], v[34:35], v[40:41], v[38:39] op_sel_hi:[1,0,1]
	v_pk_fma_f32 v[126:127], v[34:35], v[132:133], v[36:37] op_sel_hi:[1,0,1]
	ds_read_b128 v[36:39], v43
	v_mov_b32_e32 v146, v149
	v_pk_fma_f32 v[172:173], v[34:35], v[46:47], v[44:45] op_sel_hi:[1,0,1]
	v_mov_b32_e32 v44, s14
	v_pk_fma_f32 v[88:89], v[34:35], v[102:103], v[100:101] op_sel_hi:[1,0,1]
	v_pk_fma_f32 v[92:93], v[34:35], v[110:111], v[114:115] op_sel_hi:[1,0,1]
	v_pk_fma_f32 v[114:115], v[34:35], v[144:145], v[22:23] op_sel_hi:[1,0,1]
	v_pk_fma_f32 v[112:113], v[34:35], v[146:147], v[20:21] op_sel_hi:[1,0,1]
	ds_read_b128 v[20:23], v44
	v_pk_fma_f32 v[110:111], v[34:35], v[148:149], v[18:19] op_sel_hi:[1,0,1]
	v_mov_b32_e32 v45, s15
	v_pk_fma_f32 v[184:185], v[34:35], v[66:67], v[62:63] op_sel_hi:[1,0,1]
	ds_read_b128 v[40:43], v45
	v_mov_b32_e32 v46, s16
	v_mov_b32_e32 v48, s17
	v_pk_fma_f32 v[182:183], v[34:35], v[52:53], v[60:61] op_sel_hi:[1,0,1]
	v_mov_b32_e32 v52, s18
	v_pk_fma_f32 v[188:189], v[34:35], v[64:65], v[72:73] op_sel_hi:[1,0,1]
	v_mov_b32_e32 v142, v145
	v_pk_fma_f32 v[176:177], v[34:35], v[54:55], v[50:51] op_sel_hi:[1,0,1]
	v_mov_b32_e32 v53, s19
	v_pk_fma_f32 v[186:187], v[34:35], v[70:71], v[68:69] op_sel_hi:[1,0,1]
	ds_read_b128 v[44:47], v46
	ds_read_b128 v[48:51], v48
	s_waitcnt lgkmcnt(7)
	v_mov_b32_e32 v66, v3
	v_pk_fma_f32 v[116:117], v[34:35], v[142:143], v[24:25] op_sel_hi:[1,0,1]
	v_mov_b32_e32 v54, s20
	v_mov_b32_e32 v76, v77
	v_mov_b32_e32 v55, s21
	v_pk_fma_f32 v[150:151], v[34:35], v[106:107], v[104:105] op_sel_hi:[1,0,1]
	v_pk_fma_f32 v[190:191], v[34:35], v[76:77], v[74:75] op_sel_hi:[1,0,1]
	s_waitcnt lgkmcnt(6)
	v_mov_b32_e32 v74, v29
	v_mov_b32_e32 v154, v155
	v_pk_fma_f32 v[180:181], v[34:35], v[58:59], v[56:57] op_sel_hi:[1,0,1]
	v_mov_b32_e32 v56, s22
	v_mov_b32_e32 v57, s23
	v_pk_fma_f32 v[68:69], v[34:35], v[154:155], v[152:153] op_sel_hi:[1,0,1]
	v_pk_fma_f32 v[60:61], v[34:35], v[160:161], v[158:159] op_sel_hi:[1,0,1]
	s_waitcnt lgkmcnt(5)
	v_mov_b32_e32 v64, v33
	v_mov_b32_e32 v65, s24
	v_mov_b32_e32 v67, s25
	v_mov_b32_e32 v75, s26
	v_mov_b32_e32 v85, s27
	s_waitcnt lgkmcnt(2)
	v_mov_b32_e32 v96, v43
	v_mov_b32_e32 v97, s28
	v_mov_b32_e32 v101, s29
	s_waitcnt lgkmcnt(1)
	v_mov_b32_e32 v102, v47
	v_mov_b32_e32 v103, s30
	s_waitcnt lgkmcnt(0)
	v_mov_b32_e32 v100, v51
	s_add_i32 s6, s3, 0xffff4fe0
	s_add_i32 s7, s3, 0xffff5fe0
	s_add_i32 s8, s3, 0xfffe0ff0
	s_add_i32 s9, s3, 0xfffe1ff0
	s_add_i32 s14, s3, 0xfffe2ff0
	s_waitcnt vmcnt(15)
	v_mov_b32_e32 v78, v228
	v_mov_b32_e32 v79, v229
	s_mov_b32 s44, 0xfff7c000
	v_lshl_add_u64 v[206:207], v[208:209], 0, s[44:45]
	global_load_dwordx2 v[228:229], v[206:207], off nt
	v_pk_fma_f32 v[18:19], v[78:79], v[0:1], v[156:157] op_sel_hi:[1,0,1]
	s_add_i32 s15, s3, 0xfffe3ff0
	s_waitcnt vmcnt(15)
	v_mov_b32_e32 v80, v230
	v_mov_b32_e32 v81, v231
	s_mov_b32 s44, 0xfff88000
	v_lshl_add_u64 v[206:207], v[208:209], 0, s[44:45]
	global_load_dwordx2 v[230:231], v[206:207], off nt
	v_pk_fma_f32 v[0:1], v[80:81], v[0:1], v[18:19] op_sel:[0,1,0]
	v_pk_fma_f32 v[18:19], v[78:79], v[26:27], v[88:89] op_sel_hi:[1,0,1]
	s_waitcnt vmcnt(15)
	v_mov_b32_e32 v82, v232
	v_mov_b32_e32 v83, v233
	s_mov_b32 s44, 0xfff94000
	v_lshl_add_u64 v[206:207], v[208:209], 0, s[44:45]
	global_load_dwordx2 v[232:233], v[206:207], off nt
	v_pk_fma_f32 v[62:63], v[82:83], v[2:3], v[0:1] op_sel_hi:[1,0,1]
	v_pk_fma_f32 v[0:1], v[78:79], v[30:31], v[90:91] op_sel_hi:[1,0,1]
	v_pk_fma_f32 v[18:19], v[80:81], v[26:27], v[18:19] op_sel:[0,1,0]
	v_pk_fma_f32 v[0:1], v[80:81], v[30:31], v[0:1] op_sel:[0,1,0]
	v_pk_fma_f32 v[72:73], v[82:83], v[28:29], v[18:19] op_sel_hi:[1,0,1]
	v_pk_fma_f32 v[18:19], v[78:79], v[36:37], v[86:87] op_sel_hi:[1,0,1]
	v_pk_fma_f32 v[70:71], v[82:83], v[32:33], v[0:1] op_sel_hi:[1,0,1]
	ds_read_b128 v[0:3], v52
	ds_read_b128 v[24:27], v53
	v_pk_fma_f32 v[18:19], v[80:81], v[36:37], v[18:19] op_sel:[0,1,0]
	v_mov_b32_e32 v88, v23
	v_pk_fma_f32 v[86:87], v[82:83], v[38:39], v[18:19] op_sel_hi:[1,0,1]
	v_pk_fma_f32 v[18:19], v[78:79], v[20:21], v[92:93] op_sel_hi:[1,0,1]
	ds_read_b128 v[28:31], v55
	v_pk_fma_f32 v[18:19], v[80:81], v[20:21], v[18:19] op_sel:[0,1,0]
	s_waitcnt lgkmcnt(2)
	v_pk_fma_f32 v[16:17], v[78:79], v[0:1], v[16:17] op_sel_hi:[1,0,1]
	v_pk_fma_f32 v[92:93], v[82:83], v[22:23], v[18:19] op_sel_hi:[1,0,1]
	ds_read_b128 v[18:21], v54
	v_pk_fma_f32 v[22:23], v[78:79], v[40:41], v[94:95] op_sel_hi:[1,0,1]
	v_pk_fma_f32 v[0:1], v[80:81], v[0:1], v[16:17] op_sel:[0,1,0]
	v_pk_fma_f32 v[22:23], v[80:81], v[40:41], v[22:23] op_sel:[0,1,0]
	s_waitcnt lgkmcnt(2)
	v_pk_fma_f32 v[16:17], v[78:79], v[24:25], v[150:151] op_sel_hi:[1,0,1]
	v_pk_fma_f32 v[94:95], v[82:83], v[42:43], v[22:23] op_sel_hi:[1,0,1]
	v_pk_fma_f32 v[22:23], v[78:79], v[44:45], v[98:99] op_sel_hi:[1,0,1]
	ds_read_b128 v[32:35], v56
	v_pk_fma_f32 v[22:23], v[80:81], v[44:45], v[22:23] op_sel:[0,1,0]
	v_pk_fma_f32 v[106:107], v[82:83], v[2:3], v[0:1] op_sel_hi:[1,0,1]
	v_pk_fma_f32 v[98:99], v[82:83], v[46:47], v[22:23] op_sel_hi:[1,0,1]
	v_pk_fma_f32 v[22:23], v[78:79], v[48:49], v[108:109] op_sel_hi:[1,0,1]
	v_mov_b32_e32 v108, v3
	ds_read_b128 v[0:3], v57
	v_pk_fma_f32 v[16:17], v[80:81], v[24:25], v[16:17] op_sel:[0,1,0]
	v_pk_fma_f32 v[22:23], v[80:81], v[48:49], v[22:23] op_sel:[0,1,0]
	v_pk_fma_f32 v[76:77], v[82:83], v[26:27], v[16:17] op_sel_hi:[1,0,1]
	s_waitcnt lgkmcnt(2)
; #define LAS __attribute__((address_space(3)))
; __device__ __forceinline__ void phase0(CArgs a, LAS unsigned char* lds, int tid, int lane, int wave, int G, int bx) {
;     ...
;                 for (int i = 0; i < 16; ++i) wv[i] = __builtin_nontemporal_load((const f32x2*)(wp + (size_t)i * NMOD));
; #pragma unroll
;                 for (int q = 0; q < 4; ++q) {
; #pragma unroll
;                     for (int r = 0; r < NB; ++r) { const f32x4 s4 = *(const LAS f32x4*)(S + r * 1024 + k + 4 * q);
;                         acc[r] += wv[4 * q] * s4[0]; acc[r] += wv[4 * q + 1] * s4[1]; acc[r] += wv[4 * q + 2] * s4[2]; acc[r] += wv[4 * q + 3] * s4[3]; } }
	v_pk_fma_f32 v[16:17], v[78:79], v[18:19], v[168:169] op_sel_hi:[1,0,1]
	v_pk_fma_f32 v[104:105], v[82:83], v[50:51], v[22:23] op_sel_hi:[1,0,1]
	v_pk_fma_f32 v[16:17], v[80:81], v[18:19], v[16:17] op_sel:[0,1,0]
	v_mov_b32_e32 v84, v27
	v_pk_fma_f32 v[58:59], v[82:83], v[20:21], v[16:17] op_sel_hi:[1,0,1]
	v_pk_fma_f32 v[16:17], v[78:79], v[28:29], v[170:171] op_sel_hi:[1,0,1]
	ds_read_b128 v[24:27], v65
	v_pk_fma_f32 v[16:17], v[80:81], v[28:29], v[16:17] op_sel:[0,1,0]
	s_waitcnt lgkmcnt(1)
	v_pk_fma_f32 v[22:23], v[78:79], v[0:1], v[174:175] op_sel_hi:[1,0,1]
	v_pk_fma_f32 v[52:53], v[82:83], v[30:31], v[16:17] op_sel_hi:[1,0,1]
	v_pk_fma_f32 v[16:17], v[78:79], v[32:33], v[172:173] op_sel_hi:[1,0,1]
	v_pk_fma_f32 v[0:1], v[80:81], v[0:1], v[22:23] op_sel:[0,1,0]
	v_pk_fma_f32 v[16:17], v[80:81], v[32:33], v[16:17] op_sel:[0,1,0]
	v_mov_b32_e32 v90, v39
	ds_read_b128 v[36:39], v67
	v_pk_fma_f32 v[18:19], v[82:83], v[34:35], v[16:17] op_sel_hi:[1,0,1]
	v_mov_b32_e32 v16, v3
	v_pk_fma_f32 v[22:23], v[82:83], v[2:3], v[0:1] op_sel_hi:[1,0,1]
	ds_read_b128 v[0:3], v75
	ds_read_b128 v[40:43], v85
	s_waitcnt lgkmcnt(3)
	v_pk_fma_f32 v[28:29], v[78:79], v[24:25], v[176:177] op_sel_hi:[1,0,1]
	v_mov_b32_e32 v20, v35
	v_pk_fma_f32 v[24:25], v[80:81], v[24:25], v[28:29] op_sel:[0,1,0]
	v_mov_b32_e32 v28, v27
	v_pk_fma_f32 v[24:25], v[82:83], v[26:27], v[24:25] op_sel_hi:[1,0,1]
	s_waitcnt lgkmcnt(2)
	v_pk_fma_f32 v[26:27], v[78:79], v[36:37], v[180:181] op_sel_hi:[1,0,1]
	s_waitcnt lgkmcnt(1)
	v_pk_fma_f32 v[34:35], v[78:79], v[0:1], v[182:183] op_sel_hi:[1,0,1]
	v_pk_fma_f32 v[26:27], v[80:81], v[36:37], v[26:27] op_sel:[0,1,0]
	v_pk_fma_f32 v[0:1], v[80:81], v[0:1], v[34:35] op_sel:[0,1,0]
	v_mov_b32_e32 v54, v31
	v_pk_fma_f32 v[30:31], v[82:83], v[38:39], v[26:27] op_sel_hi:[1,0,1]
	v_mov_b32_e32 v26, v3
	v_pk_fma_f32 v[34:35], v[82:83], v[2:3], v[0:1] op_sel_hi:[1,0,1]
	ds_read_b128 v[0:3], v97
	ds_read_b128 v[46:49], v101
	v_mov_b32_e32 v32, v39
	s_waitcnt lgkmcnt(2)
	v_pk_fma_f32 v[36:37], v[78:79], v[40:41], v[184:185] op_sel_hi:[1,0,1]
	v_mov_b32_e32 v56, v21
	s_waitcnt lgkmcnt(1)
	v_pk_fma_f32 v[38:39], v[78:79], v[0:1], v[186:187] op_sel_hi:[1,0,1]
	v_pk_fma_f32 v[36:37], v[80:81], v[40:41], v[36:37] op_sel:[0,1,0]
	v_pk_fma_f32 v[0:1], v[80:81], v[0:1], v[38:39] op_sel:[0,1,0]
	v_pk_fma_f32 v[36:37], v[82:83], v[42:43], v[36:37] op_sel_hi:[1,0,1]
	v_mov_b32_e32 v40, v43
	v_pk_fma_f32 v[42:43], v[82:83], v[2:3], v[0:1] op_sel_hi:[1,0,1]
	s_waitcnt lgkmcnt(0)
	v_pk_fma_f32 v[0:1], v[78:79], v[46:47], v[188:189] op_sel_hi:[1,0,1]
	v_mov_b32_e32 v44, v3
	v_pk_fma_f32 v[0:1], v[80:81], v[46:47], v[0:1] op_sel:[0,1,0]
	v_mov_b32_e32 v38, v49
	v_pk_fma_f32 v[46:47], v[82:83], v[48:49], v[0:1] op_sel_hi:[1,0,1]
	ds_read_b128 v[48:51], v103
	ds_read_b128 v[0:3], v133
	s_waitcnt vmcnt(15)
	v_mov_b32_e32 v14, v234
	v_mov_b32_e32 v15, v235
	s_mov_b32 s44, 0xfffa0000
	v_lshl_add_u64 v[206:207], v[208:209], 0, s[44:45]
	global_load_dwordx2 v[234:235], v[206:207], off nt
	v_pk_fma_f32 v[58:59], v[14:15], v[56:57], v[58:59] op_sel_hi:[1,0,1]
	v_pk_fma_f32 v[54:55], v[14:15], v[54:55], v[52:53] op_sel_hi:[1,0,1]
	v_pk_fma_f32 v[168:169], v[14:15], v[66:67], v[62:63] op_sel_hi:[1,0,1]
	s_waitcnt lgkmcnt(1)
	v_pk_fma_f32 v[132:133], v[78:79], v[48:49], v[190:191] op_sel_hi:[1,0,1]
	s_waitcnt lgkmcnt(0)
	v_pk_fma_f32 v[130:131], v[78:79], v[0:1], v[130:131] op_sel_hi:[1,0,1]
	v_pk_fma_f32 v[48:49], v[80:81], v[48:49], v[132:133] op_sel:[0,1,0]
	v_pk_fma_f32 v[0:1], v[80:81], v[0:1], v[130:131] op_sel:[0,1,0]
	v_pk_fma_f32 v[62:63], v[14:15], v[100:101], v[104:105] op_sel_hi:[1,0,1]
	v_pk_fma_f32 v[130:131], v[82:83], v[2:3], v[0:1] op_sel_hi:[1,0,1]
	v_mov_b32_e32 v0, s6
	v_mov_b32_e32 v1, s7
	ds_read_b128 v[132:135], v0
	ds_read_b128 v[136:139], v1
	s_add_i32 s6, s3, 0xffff6fe0
	s_add_i32 s7, s3, 0xffff7fe0
	v_mov_b32_e32 v2, v3
	s_waitcnt lgkmcnt(1)
	v_pk_fma_f32 v[0:1], v[78:79], v[132:133], v[128:129] op_sel_hi:[1,0,1]
	v_mov_b32_e32 v27, s8
	v_pk_fma_f32 v[0:1], v[80:81], v[132:133], v[0:1] op_sel:[0,1,0]
	v_mov_b32_e32 v29, s9
	v_pk_fma_f32 v[128:129], v[82:83], v[134:135], v[0:1] op_sel_hi:[1,0,1]
	s_waitcnt lgkmcnt(0)
	v_pk_fma_f32 v[0:1], v[78:79], v[136:137], v[126:127] op_sel_hi:[1,0,1]
	v_mov_b32_e32 v134, v139
	v_pk_fma_f32 v[0:1], v[80:81], v[136:137], v[0:1] op_sel:[0,1,0]
	v_pk_fma_f32 v[176:177], v[14:15], v[26:27], v[34:35] op_sel_hi:[1,0,1]
	v_pk_fma_f32 v[126:127], v[82:83], v[138:139], v[0:1] op_sel_hi:[1,0,1]
	v_mov_b32_e32 v0, s6
	v_mov_b32_e32 v1, s7
	ds_read_b128 v[136:139], v0
	ds_read_b128 v[140:143], v1
	s_add_i32 s6, s3, 0xffff8fe0
	s_add_i32 s7, s3, 0xffff9fe0
	v_mov_b32_e32 v33, s14
	s_waitcnt lgkmcnt(1)
	v_pk_fma_f32 v[0:1], v[78:79], v[136:137], v[124:125] op_sel_hi:[1,0,1]
	v_pk_fma_f32 v[174:175], v[14:15], v[32:33], v[30:31] op_sel_hi:[1,0,1]
	v_pk_fma_f32 v[0:1], v[80:81], v[136:137], v[0:1] op_sel:[0,1,0]
	s_add_i32 s16, s3, 0xfffe4ff0
	v_pk_fma_f32 v[124:125], v[82:83], v[138:139], v[0:1] op_sel_hi:[1,0,1]
	s_waitcnt lgkmcnt(0)
	v_pk_fma_f32 v[0:1], v[78:79], v[140:141], v[122:123] op_sel_hi:[1,0,1]
	v_mov_b32_e32 v138, v143
	v_pk_fma_f32 v[0:1], v[80:81], v[140:141], v[0:1] op_sel:[0,1,0]
	v_pk_fma_f32 v[48:49], v[82:83], v[50:51], v[48:49] op_sel_hi:[1,0,1]
	v_pk_fma_f32 v[122:123], v[82:83], v[142:143], v[0:1] op_sel_hi:[1,0,1]
	v_mov_b32_e32 v0, s6
	v_mov_b32_e32 v1, s7
	ds_read_b128 v[140:143], v0
	ds_read_b128 v[144:147], v1
	s_add_i32 s6, s3, 0xffffafe0
	s_add_i32 s7, s3, 0xffffbfe0
	s_add_i32 s21, s3, 0xfffe9ff0
	s_waitcnt lgkmcnt(1)
; #define LAS __attribute__((address_space(3)))
; __device__ __forceinline__ void phase0(CArgs a, LAS unsigned char* lds, int tid, int lane, int wave, int G, int bx) {
;     ...
;                 for (int i = 0; i < 16; ++i) wv[i] = __builtin_nontemporal_load((const f32x2*)(wp + (size_t)i * NMOD));
; #pragma unroll
;                 for (int q = 0; q < 4; ++q) {
; #pragma unroll
;                     for (int r = 0; r < NB; ++r) { const f32x4 s4 = *(const LAS f32x4*)(S + r * 1024 + k + 4 * q);
;                         acc[r] += wv[4 * q] * s4[0]; acc[r] += wv[4 * q + 1] * s4[1]; acc[r] += wv[4 * q + 2] * s4[2]; acc[r] += wv[4 * q + 3] * s4[3]; } }
	v_pk_fma_f32 v[0:1], v[78:79], v[140:141], v[120:121] op_sel_hi:[1,0,1]
	v_mov_b32_e32 v39, s15
	v_pk_fma_f32 v[0:1], v[80:81], v[140:141], v[0:1] op_sel:[0,1,0]
	v_mov_b32_e32 v41, s16
	v_pk_fma_f32 v[120:121], v[82:83], v[142:143], v[0:1] op_sel_hi:[1,0,1]
	s_waitcnt lgkmcnt(0)
	v_pk_fma_f32 v[0:1], v[78:79], v[144:145], v[118:119] op_sel_hi:[1,0,1]
	v_mov_b32_e32 v142, v147
	v_pk_fma_f32 v[0:1], v[80:81], v[144:145], v[0:1] op_sel:[0,1,0]
	v_mov_b32_e32 v132, v135
	v_pk_fma_f32 v[118:119], v[82:83], v[146:147], v[0:1] op_sel_hi:[1,0,1]
	v_mov_b32_e32 v0, s6
	v_mov_b32_e32 v1, s7
	ds_read_b128 v[144:147], v0
	ds_read_b128 v[148:151], v1
	s_add_i32 s6, s3, 0xffffcfe0
	s_add_i32 s7, s3, 0xffffdfe0
	v_pk_fma_f32 v[180:181], v[14:15], v[40:41], v[36:37] op_sel_hi:[1,0,1]
	s_waitcnt lgkmcnt(1)
	v_pk_fma_f32 v[0:1], v[78:79], v[144:145], v[116:117] op_sel_hi:[1,0,1]
	v_mov_b32_e32 v133, s21
	v_pk_fma_f32 v[0:1], v[80:81], v[144:145], v[0:1] op_sel:[0,1,0]
	v_pk_fma_f32 v[184:185], v[14:15], v[38:39], v[46:47] op_sel_hi:[1,0,1]
	v_pk_fma_f32 v[116:117], v[82:83], v[146:147], v[0:1] op_sel_hi:[1,0,1]
	s_waitcnt lgkmcnt(0)
	v_pk_fma_f32 v[0:1], v[78:79], v[148:149], v[114:115] op_sel_hi:[1,0,1]
	v_mov_b32_e32 v146, v151
	v_pk_fma_f32 v[0:1], v[80:81], v[148:149], v[0:1] op_sel:[0,1,0]
	s_add_i32 s17, s3, 0xfffe5ff0
	v_pk_fma_f32 v[114:115], v[82:83], v[150:151], v[0:1] op_sel_hi:[1,0,1]
	v_mov_b32_e32 v0, s6
	v_mov_b32_e32 v1, s7
	ds_read_b128 v[148:151], v0
	ds_read_b128 v[152:155], v1
	s_add_i32 s6, s3, 0xffffefe0
	s_sub_i32 s7, s3, 32
	v_mov_b32_e32 v136, v139
	s_waitcnt lgkmcnt(1)
	v_pk_fma_f32 v[0:1], v[78:79], v[148:149], v[112:113] op_sel_hi:[1,0,1]
	v_mov_b32_e32 v45, s17
	v_pk_fma_f32 v[0:1], v[80:81], v[148:149], v[0:1] op_sel:[0,1,0]
	v_mov_b32_e32 v148, v151
	v_pk_fma_f32 v[112:113], v[82:83], v[150:151], v[0:1] op_sel_hi:[1,0,1]
	s_waitcnt lgkmcnt(0)
	v_pk_fma_f32 v[0:1], v[78:79], v[152:153], v[110:111] op_sel_hi:[1,0,1]
	v_mov_b32_e32 v150, v155
	v_pk_fma_f32 v[0:1], v[80:81], v[152:153], v[0:1] op_sel:[0,1,0]
	v_pk_fma_f32 v[182:183], v[14:15], v[44:45], v[42:43] op_sel_hi:[1,0,1]
	v_pk_fma_f32 v[110:111], v[82:83], v[154:155], v[0:1] op_sel_hi:[1,0,1]
	v_mov_b32_e32 v0, s6
	v_mov_b32_e32 v1, s7
	ds_read_b128 v[152:155], v0
	ds_read_b128 v[170:173], v1
	s_mov_b32 s6, 0xfffac000
	s_add_i32 s7, s3, 0xfffdfff0
	s_add_i32 s18, s3, 0xfffe6ff0
	s_waitcnt lgkmcnt(1)
	v_pk_fma_f32 v[0:1], v[78:79], v[152:153], v[68:69] op_sel_hi:[1,0,1]
	v_mov_b32_e32 v158, v155
	v_pk_fma_f32 v[0:1], v[80:81], v[152:153], v[0:1] op_sel:[0,1,0]
	v_pk_fma_f32 v[152:153], v[14:15], v[74:75], v[72:73] op_sel_hi:[1,0,1]
	v_pk_fma_f32 v[156:157], v[82:83], v[154:155], v[0:1] op_sel_hi:[1,0,1]
	s_waitcnt lgkmcnt(0)
	v_pk_fma_f32 v[0:1], v[78:79], v[170:171], v[60:61] op_sel_hi:[1,0,1]
	v_pk_fma_f32 v[154:155], v[14:15], v[64:65], v[70:71] op_sel_hi:[1,0,1]
	v_pk_fma_f32 v[0:1], v[80:81], v[170:171], v[0:1] op_sel:[0,1,0]
	v_pk_fma_f32 v[78:79], v[14:15], v[88:89], v[92:93] op_sel_hi:[1,0,1]
	v_pk_fma_f32 v[170:171], v[82:83], v[172:173], v[0:1] op_sel_hi:[1,0,1]
	v_add_co_u32_e32 v0, vcc, s6, v12
	s_mov_b32 s6, 0xfffb8000
	s_nop 0
	v_addc_co_u32_e32 v1, vcc, -1, v13, vcc
	v_add_co_u32_e32 v64, vcc, s6, v12
	s_mov_b32 s6, 0xfffc4000
	s_nop 0
	v_addc_co_u32_e32 v65, vcc, -1, v13, vcc
	v_add_co_u32_e32 v56, vcc, s6, v12
	s_mov_b32 s6, 0xfffd0000
	s_nop 0
	v_addc_co_u32_e32 v57, vcc, -1, v13, vcc
	v_add_co_u32_e32 v52, vcc, s6, v12
	s_add_i32 s6, s3, 0xfffdeff0
	s_nop 0
	v_addc_co_u32_e32 v53, vcc, -1, v13, vcc
	s_nop 0
	v_mov_b32_e32 v3, s6
	v_pk_fma_f32 v[74:75], v[14:15], v[96:97], v[94:95] op_sel_hi:[1,0,1]
	v_pk_fma_f32 v[70:71], v[14:15], v[102:103], v[98:99] op_sel_hi:[1,0,1]
	v_pk_fma_f32 v[94:95], v[14:15], v[20:21], v[18:19] op_sel_hi:[1,0,1]
	v_pk_fma_f32 v[98:99], v[14:15], v[16:17], v[22:23] op_sel_hi:[1,0,1]
	ds_read_b128 v[16:19], v3
	v_mov_b32_e32 v20, s7
	ds_read_b128 v[20:23], v20
	v_mov_b32_e32 v160, v173
	v_pk_fma_f32 v[172:173], v[14:15], v[28:29], v[24:25] op_sel_hi:[1,0,1]
	ds_read_b128 v[24:27], v27
	ds_read_b128 v[28:31], v29
	v_pk_fma_f32 v[52:53], v[14:15], v[2:3], v[130:131] op_sel_hi:[1,0,1]
	ds_read_b128 v[32:35], v33
	ds_read_b128 v[36:39], v39
	v_pk_fma_f32 v[82:83], v[14:15], v[90:91], v[86:87] op_sel_hi:[1,0,1]
	v_pk_fma_f32 v[90:91], v[14:15], v[148:149], v[112:113] op_sel_hi:[1,0,1]
	v_pk_fma_f32 v[56:57], v[14:15], v[132:133], v[128:129] op_sel_hi:[1,0,1]
	v_pk_fma_f32 v[64:65], v[14:15], v[136:137], v[124:125] op_sel_hi:[1,0,1]
	ds_read_b128 v[40:43], v41
	ds_read_b128 v[44:47], v45
	s_add_i32 s22, s3, 0xfffeaff0
	s_add_i32 s23, s3, 0xfffebff0
	s_add_i32 s24, s3, 0xfffecff0
	s_add_i32 s25, s3, 0xfffedff0
	s_add_i32 s29, s3, 0xffff1ff0
	s_add_i32 s30, s3, 0xffff2ff0
	v_mov_b32_e32 v50, v51
	v_mov_b32_e32 v140, v143
	v_mov_b32_e32 v144, v147
	v_pk_fma_f32 v[86:87], v[14:15], v[84:85], v[76:77] op_sel_hi:[1,0,1]
	v_mov_b32_e32 v51, s18
	v_mov_b32_e32 v135, s22
	v_mov_b32_e32 v139, s23
	v_mov_b32_e32 v141, s24
	v_mov_b32_e32 v147, s25
	v_mov_b32_e32 v151, s29
	v_mov_b32_e32 v159, s30
	v_pk_fma_f32 v[76:77], v[14:15], v[142:143], v[118:119] op_sel_hi:[1,0,1]
	v_pk_fma_f32 v[60:61], v[14:15], v[108:109], v[106:107] op_sel_hi:[1,0,1]
	s_add_i32 s19, s3, 0xfffe7ff0
	v_pk_fma_f32 v[186:187], v[14:15], v[50:51], v[48:49] op_sel_hi:[1,0,1]
	v_pk_fma_f32 v[66:67], v[14:15], v[134:135], v[126:127] op_sel_hi:[1,0,1]
	v_pk_fma_f32 v[68:69], v[14:15], v[138:139], v[122:123] op_sel_hi:[1,0,1]
	v_pk_fma_f32 v[72:73], v[14:15], v[140:141], v[120:121] op_sel_hi:[1,0,1]
	v_pk_fma_f32 v[80:81], v[14:15], v[144:145], v[116:117] op_sel_hi:[1,0,1]
	v_pk_fma_f32 v[84:85], v[14:15], v[146:147], v[114:115] op_sel_hi:[1,0,1]
	v_pk_fma_f32 v[96:97], v[14:15], v[150:151], v[110:111] op_sel_hi:[1,0,1]
	v_pk_fma_f32 v[110:111], v[14:15], v[158:159], v[156:157] op_sel_hi:[1,0,1]
	v_pk_fma_f32 v[102:103], v[14:15], v[160:161], v[170:171] op_sel_hi:[1,0,1]
	v_mov_b32_e32 v107, s19
	s_add_i32 s20, s3, 0xfffe8ff0
	s_waitcnt lgkmcnt(7)
; #define LAS __attribute__((address_space(3)))
; __device__ __forceinline__ void phase0(CArgs a, LAS unsigned char* lds, int tid, int lane, int wave, int G, int bx) {
;     ...
;                 for (int i = 0; i < 16; ++i) wv[i] = __builtin_nontemporal_load((const f32x2*)(wp + (size_t)i * NMOD));
; #pragma unroll
;                 for (int q = 0; q < 4; ++q) {
; #pragma unroll
;                     for (int r = 0; r < NB; ++r) { const f32x4 s4 = *(const LAS f32x4*)(S + r * 1024 + k + 4 * q);
;                         acc[r] += wv[4 * q] * s4[0]; acc[r] += wv[4 * q + 1] * s4[1]; acc[r] += wv[4 * q + 2] * s4[2]; acc[r] += wv[4 * q + 3] * s4[3]; } }
	v_mov_b32_e32 v108, v19
	v_mov_b32_e32 v109, s20
	s_waitcnt lgkmcnt(6)
	v_mov_b32_e32 v106, v23
	s_waitcnt lgkmcnt(4)
	v_mov_b32_e32 v140, v31
	s_waitcnt lgkmcnt(3)
	v_mov_b32_e32 v138, v35
	v_mov_b32_e32 v132, v27
	s_add_i32 s26, s3, 0xfffeeff0
	s_waitcnt lgkmcnt(2)
	v_mov_b32_e32 v146, v39
	v_mov_b32_e32 v48, s26
	s_add_i32 s27, s3, 0xfffefff0
	s_add_i32 s28, s3, 0xffff0ff0
	v_mov_b32_e32 v49, s27
	v_mov_b32_e32 v50, s28
	s_waitcnt lgkmcnt(0)
	v_mov_b32_e32 v150, v47
	s_add_i32 s31, s3, 0xffff3ff0
	v_mov_b32_e32 v188, s31
	s_add_i32 s6, s3, 0xffff4ff0
	s_add_i32 s7, s3, 0xffff5ff0
	s_add_i32 s8, s3, 0xfffe1000
	s_add_i32 s9, s3, 0xfffe2000
	s_add_i32 s14, s3, 0xfffe3000
	s_add_i32 s17, s3, 0xfffe6000
	s_add_i32 s15, s3, 0xfffe4000
	s_add_i32 s16, s3, 0xfffe5000
	s_add_i32 s18, s3, 0xfffe7000
	s_waitcnt vmcnt(15)
	v_mov_b32_e32 v88, v236
	v_mov_b32_e32 v89, v237
	s_mov_b32 s44, 0xfffac000
	v_lshl_add_u64 v[206:207], v[208:209], 0, s[44:45]
	global_load_dwordx2 v[236:237], v[206:207], off nt
	v_pk_fma_f32 v[2:3], v[88:89], v[16:17], v[168:169] op_sel_hi:[1,0,1]
	s_add_i32 s19, s3, 0xfffe8000
	s_waitcnt vmcnt(15)
	v_mov_b32_e32 v92, v238
	v_mov_b32_e32 v93, v239
	s_mov_b32 s44, 0xfffb8000
	v_lshl_add_u64 v[206:207], v[208:209], 0, s[44:45]
	global_load_dwordx2 v[238:239], v[206:207], off nt
	v_pk_fma_f32 v[2:3], v[92:93], v[16:17], v[2:3] op_sel:[0,1,0]
	ds_read_b128 v[14:17], v51
	s_waitcnt vmcnt(15)
	v_mov_b32_e32 v100, v240
	v_mov_b32_e32 v101, v241
	s_mov_b32 s44, 0xfffc4000
	v_lshl_add_u64 v[206:207], v[208:209], 0, s[44:45]
	global_load_dwordx2 v[240:241], v[206:207], off nt
	v_pk_fma_f32 v[104:105], v[100:101], v[18:19], v[2:3] op_sel_hi:[1,0,1]
	v_pk_fma_f32 v[2:3], v[88:89], v[20:21], v[154:155] op_sel_hi:[1,0,1]
	s_add_i32 s20, s3, 0xfffe9000
	v_pk_fma_f32 v[2:3], v[92:93], v[20:21], v[2:3] op_sel:[0,1,0]
	ds_read_b128 v[18:21], v107
	v_pk_fma_f32 v[112:113], v[100:101], v[22:23], v[2:3] op_sel_hi:[1,0,1]
	v_pk_fma_f32 v[2:3], v[88:89], v[24:25], v[152:153] op_sel_hi:[1,0,1]
	v_mov_b32_e32 v152, v43
	v_pk_fma_f32 v[2:3], v[92:93], v[24:25], v[2:3] op_sel:[0,1,0]
	ds_read_b128 v[22:25], v109
	v_pk_fma_f32 v[128:129], v[100:101], v[26:27], v[2:3] op_sel_hi:[1,0,1]
	v_pk_fma_f32 v[2:3], v[88:89], v[28:29], v[82:83] op_sel_hi:[1,0,1]
	s_waitcnt lgkmcnt(2)
	v_mov_b32_e32 v158, v17
	v_pk_fma_f32 v[2:3], v[92:93], v[28:29], v[2:3] op_sel:[0,1,0]
	ds_read_b128 v[26:29], v133
	v_pk_fma_f32 v[136:137], v[100:101], v[30:31], v[2:3] op_sel_hi:[1,0,1]
	v_pk_fma_f32 v[2:3], v[88:89], v[32:33], v[78:79] op_sel_hi:[1,0,1]
	s_waitcnt lgkmcnt(1)
	v_mov_b32_e32 v124, v25
	v_pk_fma_f32 v[2:3], v[92:93], v[32:33], v[2:3] op_sel:[0,1,0]
	ds_read_b128 v[30:33], v135
	v_pk_fma_f32 v[142:143], v[100:101], v[34:35], v[2:3] op_sel_hi:[1,0,1]
	v_pk_fma_f32 v[2:3], v[88:89], v[36:37], v[74:75] op_sel_hi:[1,0,1]
	v_mov_b32_e32 v134, v21
	v_pk_fma_f32 v[2:3], v[92:93], v[36:37], v[2:3] op_sel:[0,1,0]
	ds_read_b128 v[34:37], v139
	v_pk_fma_f32 v[144:145], v[100:101], v[38:39], v[2:3] op_sel_hi:[1,0,1]
	v_pk_fma_f32 v[2:3], v[88:89], v[40:41], v[70:71] op_sel_hi:[1,0,1]
	s_waitcnt vmcnt(15)
	v_mov_b32_e32 v0, v242
	v_mov_b32_e32 v1, v243
	s_mov_b32 s44, 0xfffd0000
	v_lshl_add_u64 v[206:207], v[208:209], 0, s[44:45]
	global_load_dwordx2 v[242:243], v[206:207], off nt
	v_pk_fma_f32 v[112:113], v[0:1], v[106:107], v[112:113] op_sel_hi:[1,0,1]
	v_pk_fma_f32 v[2:3], v[92:93], v[40:41], v[2:3] op_sel:[0,1,0]
	ds_read_b128 v[38:41], v141
	v_pk_fma_f32 v[148:149], v[100:101], v[42:43], v[2:3] op_sel_hi:[1,0,1]
	v_pk_fma_f32 v[2:3], v[88:89], v[44:45], v[62:63] op_sel_hi:[1,0,1]
	s_add_i32 s21, s3, 0xfffea000
	v_pk_fma_f32 v[2:3], v[92:93], v[44:45], v[2:3] op_sel:[0,1,0]
	ds_read_b128 v[42:45], v147
	v_pk_fma_f32 v[154:155], v[100:101], v[46:47], v[2:3] op_sel_hi:[1,0,1]
	v_pk_fma_f32 v[2:3], v[88:89], v[14:15], v[60:61] op_sel_hi:[1,0,1]
	s_add_i32 s22, s3, 0xfffeb000
	v_pk_fma_f32 v[2:3], v[92:93], v[14:15], v[2:3] op_sel:[0,1,0]
	s_waitcnt lgkmcnt(3)
	v_pk_fma_f32 v[14:15], v[88:89], v[30:31], v[94:95] op_sel_hi:[1,0,1]
	v_pk_fma_f32 v[156:157], v[100:101], v[16:17], v[2:3] op_sel_hi:[1,0,1]
	v_pk_fma_f32 v[2:3], v[88:89], v[18:19], v[86:87] op_sel_hi:[1,0,1]
	v_pk_fma_f32 v[14:15], v[92:93], v[30:31], v[14:15] op_sel:[0,1,0]
	v_pk_fma_f32 v[2:3], v[92:93], v[18:19], v[2:3] op_sel:[0,1,0]
	v_pk_fma_f32 v[18:19], v[100:101], v[32:33], v[14:15] op_sel_hi:[1,0,1]
	v_pk_fma_f32 v[130:131], v[100:101], v[20:21], v[2:3] op_sel_hi:[1,0,1]
	v_pk_fma_f32 v[2:3], v[88:89], v[22:23], v[58:59] op_sel_hi:[1,0,1]
	s_waitcnt lgkmcnt(2)
	v_mov_b32_e32 v14, v37
	v_pk_fma_f32 v[2:3], v[92:93], v[22:23], v[2:3] op_sel:[0,1,0]
	v_pk_fma_f32 v[22:23], v[88:89], v[34:35], v[98:99] op_sel_hi:[1,0,1]
	v_pk_fma_f32 v[126:127], v[100:101], v[24:25], v[2:3] op_sel_hi:[1,0,1]
	v_pk_fma_f32 v[22:23], v[92:93], v[34:35], v[22:23] op_sel:[0,1,0]
	v_pk_fma_f32 v[2:3], v[88:89], v[26:27], v[54:55] op_sel_hi:[1,0,1]
	v_pk_fma_f32 v[22:23], v[100:101], v[36:37], v[22:23] op_sel_hi:[1,0,1]
	ds_read_b128 v[34:37], v48
	s_waitcnt lgkmcnt(2)
	v_pk_fma_f32 v[24:25], v[88:89], v[38:39], v[172:173] op_sel_hi:[1,0,1]
	v_pk_fma_f32 v[2:3], v[92:93], v[26:27], v[2:3] op_sel:[0,1,0]
	v_pk_fma_f32 v[24:25], v[92:93], v[38:39], v[24:25] op_sel:[0,1,0]
	s_waitcnt lgkmcnt(1)
	v_pk_fma_f32 v[26:27], v[88:89], v[42:43], v[174:175] op_sel_hi:[1,0,1]
	v_pk_fma_f32 v[2:3], v[100:101], v[28:29], v[2:3] op_sel_hi:[1,0,1]
	v_pk_fma_f32 v[24:25], v[100:101], v[40:41], v[24:25] op_sel_hi:[1,0,1]
	v_mov_b32_e32 v28, v41
	ds_read_b128 v[38:41], v49
	v_pk_fma_f32 v[26:27], v[92:93], v[42:43], v[26:27] op_sel:[0,1,0]
	s_waitcnt lgkmcnt(1)
; #define LAS __attribute__((address_space(3)))
; __device__ __forceinline__ void phase0(CArgs a, LAS unsigned char* lds, int tid, int lane, int wave, int G, int bx) {
;     ...
;                 for (int i = 0; i < 16; ++i) wv[i] = __builtin_nontemporal_load((const f32x2*)(wp + (size_t)i * NMOD));
; #pragma unroll
;                 for (int q = 0; q < 4; ++q) {
; #pragma unroll
;                     for (int r = 0; r < NB; ++r) { const f32x4 s4 = *(const LAS f32x4*)(S + r * 1024 + k + 4 * q);
;                         acc[r] += wv[4 * q] * s4[0]; acc[r] += wv[4 * q + 1] * s4[1]; acc[r] += wv[4 * q + 2] * s4[2]; acc[r] += wv[4 * q + 3] * s4[3]; } }
	v_pk_fma_f32 v[42:43], v[88:89], v[34:35], v[176:177] op_sel_hi:[1,0,1]
	v_pk_fma_f32 v[30:31], v[100:101], v[44:45], v[26:27] op_sel_hi:[1,0,1]
	v_mov_b32_e32 v32, v45
	v_pk_fma_f32 v[34:35], v[92:93], v[34:35], v[42:43] op_sel:[0,1,0]
	ds_read_b128 v[42:45], v50
	ds_read_b128 v[46:49], v151
	v_mov_b32_e32 v26, v37
	v_pk_fma_f32 v[34:35], v[100:101], v[36:37], v[34:35] op_sel_hi:[1,0,1]
	s_waitcnt lgkmcnt(2)
	v_pk_fma_f32 v[36:37], v[88:89], v[38:39], v[180:181] op_sel_hi:[1,0,1]
	v_mov_b32_e32 v15, s6
	v_pk_fma_f32 v[36:37], v[92:93], v[38:39], v[36:37] op_sel:[0,1,0]
	s_waitcnt lgkmcnt(1)
	v_pk_fma_f32 v[38:39], v[88:89], v[42:43], v[182:183] op_sel_hi:[1,0,1]
	s_waitcnt lgkmcnt(0)
	v_pk_fma_f32 v[50:51], v[88:89], v[46:47], v[184:185] op_sel_hi:[1,0,1]
	v_pk_fma_f32 v[38:39], v[92:93], v[42:43], v[38:39] op_sel:[0,1,0]
	v_pk_fma_f32 v[46:47], v[92:93], v[46:47], v[50:51] op_sel:[0,1,0]
	v_pk_fma_f32 v[42:43], v[100:101], v[44:45], v[38:39] op_sel_hi:[1,0,1]
	v_mov_b32_e32 v38, v49
	v_pk_fma_f32 v[46:47], v[100:101], v[48:49], v[46:47] op_sel_hi:[1,0,1]
	ds_read_b128 v[48:51], v159
	ds_read_b128 v[58:61], v188
	v_mov_b32_e32 v17, s7
	s_add_i32 s6, s3, 0xffff6ff0
	s_add_i32 s7, s3, 0xffff7ff0
	s_waitcnt lgkmcnt(1)
	v_pk_fma_f32 v[54:55], v[88:89], v[48:49], v[186:187] op_sel_hi:[1,0,1]
	s_waitcnt lgkmcnt(0)
	v_pk_fma_f32 v[52:53], v[88:89], v[58:59], v[52:53] op_sel_hi:[1,0,1]
	v_pk_fma_f32 v[48:49], v[92:93], v[48:49], v[54:55] op_sel:[0,1,0]
	v_pk_fma_f32 v[52:53], v[92:93], v[58:59], v[52:53] op_sel:[0,1,0]
	v_mov_b32_e32 v54, v61
	v_pk_fma_f32 v[52:53], v[100:101], v[60:61], v[52:53] op_sel_hi:[1,0,1]
	ds_read_b128 v[58:61], v15
	ds_read_b128 v[114:117], v17
	v_mov_b32_e32 v15, s6
	v_mov_b32_e32 v17, s7
	s_add_i32 s6, s3, 0xffff8ff0
	s_waitcnt lgkmcnt(1)
	v_pk_fma_f32 v[56:57], v[88:89], v[58:59], v[56:57] op_sel_hi:[1,0,1]
	s_waitcnt lgkmcnt(0)
	v_mov_b32_e32 v62, v117
	v_pk_fma_f32 v[56:57], v[92:93], v[58:59], v[56:57] op_sel:[0,1,0]
	v_mov_b32_e32 v58, v61
	v_pk_fma_f32 v[56:57], v[100:101], v[60:61], v[56:57] op_sel_hi:[1,0,1]
	v_pk_fma_f32 v[60:61], v[88:89], v[114:115], v[66:67] op_sel_hi:[1,0,1]
	s_add_i32 s7, s3, 0xffff9ff0
	v_pk_fma_f32 v[60:61], v[92:93], v[114:115], v[60:61] op_sel:[0,1,0]
	v_pk_fma_f32 v[176:177], v[0:1], v[124:125], v[126:127] op_sel_hi:[1,0,1]
	v_pk_fma_f32 v[60:61], v[100:101], v[116:117], v[60:61] op_sel_hi:[1,0,1]
	ds_read_b128 v[114:117], v15
	ds_read_b128 v[118:121], v17
	v_mov_b32_e32 v15, s6
	v_mov_b32_e32 v17, s7
	s_add_i32 s6, s3, 0xffffaff0
	s_waitcnt lgkmcnt(1)
	v_pk_fma_f32 v[64:65], v[88:89], v[114:115], v[64:65] op_sel_hi:[1,0,1]
	s_waitcnt lgkmcnt(0)
	v_pk_fma_f32 v[68:69], v[88:89], v[118:119], v[68:69] op_sel_hi:[1,0,1]
	v_pk_fma_f32 v[64:65], v[92:93], v[114:115], v[64:65] op_sel:[0,1,0]
	v_pk_fma_f32 v[68:69], v[92:93], v[118:119], v[68:69] op_sel:[0,1,0]
	v_pk_fma_f32 v[64:65], v[100:101], v[116:117], v[64:65] op_sel_hi:[1,0,1]
	v_mov_b32_e32 v66, v117
	v_pk_fma_f32 v[68:69], v[100:101], v[120:121], v[68:69] op_sel_hi:[1,0,1]
	v_mov_b32_e32 v70, v121
	ds_read_b128 v[114:117], v15
	ds_read_b128 v[118:121], v17
	s_add_i32 s7, s3, 0xffffbff0
	v_mov_b32_e32 v15, s6
	v_mov_b32_e32 v17, s7
	s_waitcnt lgkmcnt(1)
	v_pk_fma_f32 v[72:73], v[88:89], v[114:115], v[72:73] op_sel_hi:[1,0,1]
	s_waitcnt lgkmcnt(0)
	v_pk_fma_f32 v[76:77], v[88:89], v[118:119], v[76:77] op_sel_hi:[1,0,1]
	v_pk_fma_f32 v[72:73], v[92:93], v[114:115], v[72:73] op_sel:[0,1,0]
	v_pk_fma_f32 v[76:77], v[92:93], v[118:119], v[76:77] op_sel:[0,1,0]
	v_pk_fma_f32 v[72:73], v[100:101], v[116:117], v[72:73] op_sel_hi:[1,0,1]
	v_mov_b32_e32 v74, v117
	v_pk_fma_f32 v[76:77], v[100:101], v[120:121], v[76:77] op_sel_hi:[1,0,1]
	v_mov_b32_e32 v78, v121
	ds_read_b128 v[114:117], v15
	ds_read_b128 v[118:121], v17
	s_add_i32 s6, s3, 0xffffcff0
	s_add_i32 s7, s3, 0xffffdff0
	v_mov_b32_e32 v15, s6
	s_waitcnt lgkmcnt(1)
	v_pk_fma_f32 v[80:81], v[88:89], v[114:115], v[80:81] op_sel_hi:[1,0,1]
	s_waitcnt lgkmcnt(0)
	v_pk_fma_f32 v[84:85], v[88:89], v[118:119], v[84:85] op_sel_hi:[1,0,1]
	v_pk_fma_f32 v[80:81], v[92:93], v[114:115], v[80:81] op_sel:[0,1,0]
	v_pk_fma_f32 v[84:85], v[92:93], v[118:119], v[84:85] op_sel:[0,1,0]
	v_pk_fma_f32 v[80:81], v[100:101], v[116:117], v[80:81] op_sel_hi:[1,0,1]
	v_mov_b32_e32 v82, v117
	v_pk_fma_f32 v[84:85], v[100:101], v[120:121], v[84:85] op_sel_hi:[1,0,1]
	v_mov_b32_e32 v86, v121
	v_mov_b32_e32 v17, s7
	ds_read_b128 v[114:117], v15
	ds_read_b128 v[118:121], v17
	s_add_i32 s6, s3, 0xffffeff0
	s_add_i32 s7, s3, -16
	v_mov_b32_e32 v15, s6
	s_waitcnt lgkmcnt(1)
	v_pk_fma_f32 v[90:91], v[88:89], v[114:115], v[90:91] op_sel_hi:[1,0,1]
	s_waitcnt lgkmcnt(0)
	v_pk_fma_f32 v[96:97], v[88:89], v[118:119], v[96:97] op_sel_hi:[1,0,1]
	v_pk_fma_f32 v[90:91], v[92:93], v[114:115], v[90:91] op_sel:[0,1,0]
	v_pk_fma_f32 v[96:97], v[92:93], v[118:119], v[96:97] op_sel:[0,1,0]
	v_pk_fma_f32 v[90:91], v[100:101], v[116:117], v[90:91] op_sel_hi:[1,0,1]
	v_mov_b32_e32 v94, v117
	v_pk_fma_f32 v[96:97], v[100:101], v[120:121], v[96:97] op_sel_hi:[1,0,1]
	v_mov_b32_e32 v98, v121
	v_mov_b32_e32 v17, s7
	ds_read_b128 v[114:117], v15
	ds_read_b128 v[120:123], v17
	s_mov_b32 s6, 0xfffdc000
	v_mov_b32_e32 v16, v29
	s_add_i32 s7, s3, 0xfffe0000
	s_waitcnt lgkmcnt(1)
; #define LAS __attribute__((address_space(3)))
; __device__ __forceinline__ void phase0(CArgs a, LAS unsigned char* lds, int tid, int lane, int wave, int G, int bx) {
;     ...
;                 for (int i = 0; i < 16; ++i) wv[i] = __builtin_nontemporal_load((const f32x2*)(wp + (size_t)i * NMOD));
; #pragma unroll
;                 for (int q = 0; q < 4; ++q) {
; #pragma unroll
;                     for (int r = 0; r < NB; ++r) { const f32x4 s4 = *(const LAS f32x4*)(S + r * 1024 + k + 4 * q);
;                         acc[r] += wv[4 * q] * s4[0]; acc[r] += wv[4 * q + 1] * s4[1]; acc[r] += wv[4 * q + 2] * s4[2]; acc[r] += wv[4 * q + 3] * s4[3]; } }
	v_pk_fma_f32 v[110:111], v[88:89], v[114:115], v[110:111] op_sel_hi:[1,0,1]
	v_mov_b32_e32 v118, v117
	v_pk_fma_f32 v[110:111], v[92:93], v[114:115], v[110:111] op_sel:[0,1,0]
	v_pk_fma_f32 v[180:181], v[0:1], v[16:17], v[2:3] op_sel_hi:[1,0,1]
	v_pk_fma_f32 v[114:115], v[100:101], v[116:117], v[110:111] op_sel_hi:[1,0,1]
	v_pk_fma_f32 v[110:111], v[0:1], v[132:133], v[128:129] op_sel_hi:[1,0,1]
	v_add_co_u32_e32 v128, vcc, s6, v12
	s_mov_b32 s6, 0xfffe8000
	s_nop 0
	v_addc_co_u32_e32 v129, vcc, -1, v13, vcc
	v_pk_fma_f32 v[116:117], v[0:1], v[108:109], v[104:105] op_sel_hi:[1,0,1]
	v_pk_fma_f32 v[108:109], v[0:1], v[134:135], v[130:131] op_sel_hi:[1,0,1]
	v_add_co_u32_e32 v130, vcc, s6, v12
	s_mov_b32 s6, 0xffff4000
	s_nop 0
	v_addc_co_u32_e32 v131, vcc, -1, v13, vcc
	v_add_co_u32_e32 v124, vcc, s6, v12
	s_add_i32 s6, s3, 0xfffdf000
	s_nop 0
	v_addc_co_u32_e32 v125, vcc, -1, v13, vcc
	s_nop 0
	s_nop 0
	v_mov_b32_e32 v2, s6
	v_mov_b32_e32 v20, v33
	v_mov_b32_e32 v3, s7
	v_pk_fma_f32 v[184:185], v[0:1], v[14:15], v[22:23] op_sel_hi:[1,0,1]
	ds_read_b128 v[14:17], v2
	v_pk_fma_f32 v[182:183], v[0:1], v[20:21], v[18:19] op_sel_hi:[1,0,1]
	v_mov_b32_e32 v27, s8
	v_mov_b32_e32 v29, s9
	ds_read_b128 v[18:21], v3
	v_pk_fma_f32 v[186:187], v[0:1], v[28:29], v[24:25] op_sel_hi:[1,0,1]
	ds_read_b128 v[22:25], v27
	v_mov_b32_e32 v33, s14
	v_mov_b32_e32 v44, v45
	s_waitcnt lgkmcnt(3)
	v_pk_fma_f32 v[88:89], v[88:89], v[120:121], v[102:103] op_sel_hi:[1,0,1]
	v_mov_b32_e32 v45, s17
	v_pk_fma_f32 v[188:189], v[0:1], v[32:33], v[30:31] op_sel_hi:[1,0,1]
	v_pk_fma_f32 v[190:191], v[0:1], v[26:27], v[34:35] op_sel_hi:[1,0,1]
	ds_read_b128 v[30:33], v33
	ds_read_b128 v[26:29], v29
	v_pk_fma_f32 v[36:37], v[100:101], v[40:41], v[36:37] op_sel_hi:[1,0,1]
	v_mov_b32_e32 v40, v41
	v_pk_fma_f32 v[88:89], v[92:93], v[120:121], v[88:89] op_sel:[0,1,0]
	s_add_i32 s23, s3, 0xfffec000
	s_add_i32 s25, s3, 0xfffee000
	s_add_i32 s27, s3, 0xffff0000
	s_add_i32 s28, s3, 0xffff1000
	s_add_i32 s29, s3, 0xffff2000
	s_add_i32 s30, s3, 0xffff3000
	v_mov_b32_e32 v39, s15
	v_mov_b32_e32 v41, s16
	v_pk_fma_f32 v[194:195], v[0:1], v[44:45], v[42:43] op_sel_hi:[1,0,1]
	v_pk_fma_f32 v[48:49], v[100:101], v[50:51], v[48:49] op_sel_hi:[1,0,1]
	v_mov_b32_e32 v50, v51
	v_pk_fma_f32 v[120:121], v[100:101], v[122:123], v[88:89] op_sel_hi:[1,0,1]
	v_mov_b32_e32 v122, v123
	v_mov_b32_e32 v51, s18
	v_mov_b32_e32 v55, s19
	v_mov_b32_e32 v59, s20
	v_mov_b32_e32 v63, s21
	v_pk_fma_f32 v[192:193], v[0:1], v[40:41], v[36:37] op_sel_hi:[1,0,1]
	v_mov_b32_e32 v67, s22
	v_mov_b32_e32 v71, s23
	v_mov_b32_e32 v75, s25
	v_mov_b32_e32 v95, s27
	v_mov_b32_e32 v99, s28
	v_mov_b32_e32 v119, s29
	v_mov_b32_e32 v123, s30
	ds_read_b128 v[34:37], v39
	v_pk_fma_f32 v[106:107], v[0:1], v[140:141], v[136:137] op_sel_hi:[1,0,1]
	v_pk_fma_f32 v[104:105], v[0:1], v[138:139], v[142:143] op_sel_hi:[1,0,1]
	v_pk_fma_f32 v[102:103], v[0:1], v[146:147], v[144:145] op_sel_hi:[1,0,1]
	v_pk_fma_f32 v[100:101], v[0:1], v[152:153], v[148:149] op_sel_hi:[1,0,1]
	v_pk_fma_f32 v[92:93], v[0:1], v[150:151], v[154:155] op_sel_hi:[1,0,1]
	v_pk_fma_f32 v[88:89], v[0:1], v[158:159], v[156:157] op_sel_hi:[1,0,1]
	v_pk_fma_f32 v[196:197], v[0:1], v[38:39], v[46:47] op_sel_hi:[1,0,1]
	v_pk_fma_f32 v[198:199], v[0:1], v[50:51], v[48:49] op_sel_hi:[1,0,1]
	v_pk_fma_f32 v[200:201], v[0:1], v[54:55], v[52:53] op_sel_hi:[1,0,1]
	v_pk_fma_f32 v[202:203], v[0:1], v[58:59], v[56:57] op_sel_hi:[1,0,1]
	v_pk_fma_f32 v[204:205], v[0:1], v[62:63], v[60:61] op_sel_hi:[1,0,1]
	v_pk_fma_f32 v[174:175], v[0:1], v[66:67], v[64:65] op_sel_hi:[1,0,1]
	v_pk_fma_f32 v[172:173], v[0:1], v[70:71], v[68:69] op_sel_hi:[1,0,1]
	v_pk_fma_f32 v[170:171], v[0:1], v[74:75], v[72:73] op_sel_hi:[1,0,1]
	v_pk_fma_f32 v[168:169], v[0:1], v[78:79], v[76:77] op_sel_hi:[1,0,1]
	v_pk_fma_f32 v[158:159], v[0:1], v[82:83], v[80:81] op_sel_hi:[1,0,1]
	v_pk_fma_f32 v[156:157], v[0:1], v[86:87], v[84:85] op_sel_hi:[1,0,1]
	v_pk_fma_f32 v[154:155], v[0:1], v[94:95], v[90:91] op_sel_hi:[1,0,1]
	v_pk_fma_f32 v[152:153], v[0:1], v[98:99], v[96:97] op_sel_hi:[1,0,1]
	v_pk_fma_f32 v[124:125], v[0:1], v[118:119], v[114:115] op_sel_hi:[1,0,1]
	ds_read_b128 v[38:41], v41
	v_pk_fma_f32 v[86:87], v[0:1], v[122:123], v[120:121] op_sel_hi:[1,0,1]
	ds_read_b128 v[0:3], v45
	s_waitcnt lgkmcnt(7)
	v_mov_b32_e32 v74, v17
	s_waitcnt lgkmcnt(6)
	v_mov_b32_e32 v80, v21
	s_waitcnt lgkmcnt(5)
	v_mov_b32_e32 v84, v25
	s_waitcnt lgkmcnt(3)
	v_mov_b32_e32 v132, v29
	s_add_i32 s24, s3, 0xfffed000
	v_mov_b32_e32 v138, v33
	s_waitcnt vmcnt(15)
	v_mov_b32_e32 v126, v244
	v_mov_b32_e32 v127, v245
	s_mov_b32 s44, 0xfffdc000
	v_lshl_add_u64 v[206:207], v[208:209], 0, s[44:45]
	global_load_dwordx2 v[244:245], v[206:207], off nt
	v_pk_fma_f32 v[42:43], v[126:127], v[14:15], v[116:117] op_sel_hi:[1,0,1]
	v_mov_b32_e32 v44, s24
	s_waitcnt vmcnt(15)
	v_mov_b32_e32 v128, v246
	v_mov_b32_e32 v129, v247
	s_mov_b32 s44, 0xfffe8000
	v_lshl_add_u64 v[206:207], v[208:209], 0, s[44:45]
	global_load_dwordx2 v[246:247], v[206:207], off nt
	v_pk_fma_f32 v[14:15], v[128:129], v[14:15], v[42:43] op_sel:[0,1,0]
	v_pk_fma_f32 v[42:43], v[126:127], v[18:19], v[112:113] op_sel_hi:[1,0,1]
	s_waitcnt vmcnt(15)
; #define LAS __attribute__((address_space(3)))
; __device__ __forceinline__ void phase0(CArgs a, LAS unsigned char* lds, int tid, int lane, int wave, int G, int bx) {
;     ...
;                 for (int i = 0; i < 16; ++i) wv[i] = __builtin_nontemporal_load((const f32x2*)(wp + (size_t)i * NMOD));
; #pragma unroll
;                 for (int q = 0; q < 4; ++q) {
; #pragma unroll
;                     for (int r = 0; r < NB; ++r) { const f32x4 s4 = *(const LAS f32x4*)(S + r * 1024 + k + 4 * q);
;                         acc[r] += wv[4 * q] * s4[0]; acc[r] += wv[4 * q + 1] * s4[1]; acc[r] += wv[4 * q + 2] * s4[2]; acc[r] += wv[4 * q + 3] * s4[3]; } }
	v_mov_b32_e32 v130, v248
	v_mov_b32_e32 v131, v249
	s_mov_b32 s44, 0xffff4000
	v_lshl_add_u64 v[206:207], v[208:209], 0, s[44:45]
	global_load_dwordx2 v[248:249], v[206:207], off nt
	v_pk_fma_f32 v[76:77], v[130:131], v[16:17], v[14:15] op_sel_hi:[1,0,1]
	v_pk_fma_f32 v[18:19], v[128:129], v[18:19], v[42:43] op_sel:[0,1,0]
	v_pk_fma_f32 v[42:43], v[126:127], v[22:23], v[110:111] op_sel_hi:[1,0,1]
	ds_read_b128 v[14:17], v51
	v_pk_fma_f32 v[22:23], v[128:129], v[22:23], v[42:43] op_sel:[0,1,0]
	v_pk_fma_f32 v[78:79], v[130:131], v[20:21], v[18:19] op_sel_hi:[1,0,1]
	v_pk_fma_f32 v[82:83], v[130:131], v[24:25], v[22:23] op_sel_hi:[1,0,1]
	v_pk_fma_f32 v[22:23], v[126:127], v[26:27], v[106:107] op_sel_hi:[1,0,1]
	ds_read_b128 v[18:21], v55
	v_pk_fma_f32 v[22:23], v[128:129], v[26:27], v[22:23] op_sel:[0,1,0]
	v_pk_fma_f32 v[26:27], v[126:127], v[30:31], v[104:105] op_sel_hi:[1,0,1]
	v_pk_fma_f32 v[134:135], v[130:131], v[28:29], v[22:23] op_sel_hi:[1,0,1]
	v_pk_fma_f32 v[26:27], v[128:129], v[30:31], v[26:27] op_sel:[0,1,0]
	s_waitcnt lgkmcnt(4)
	v_pk_fma_f32 v[30:31], v[126:127], v[34:35], v[102:103] op_sel_hi:[1,0,1]
	ds_read_b128 v[22:25], v59
	v_pk_fma_f32 v[30:31], v[128:129], v[34:35], v[30:31] op_sel:[0,1,0]
	s_waitcnt lgkmcnt(3)
	v_pk_fma_f32 v[34:35], v[126:127], v[0:1], v[92:93] op_sel_hi:[1,0,1]
	v_pk_fma_f32 v[136:137], v[130:131], v[32:33], v[26:27] op_sel_hi:[1,0,1]
	ds_read_b128 v[26:29], v63
	v_pk_fma_f32 v[140:141], v[130:131], v[36:37], v[30:31] op_sel_hi:[1,0,1]
	v_pk_fma_f32 v[30:31], v[126:127], v[38:39], v[100:101] op_sel_hi:[1,0,1]
	v_pk_fma_f32 v[0:1], v[128:129], v[0:1], v[34:35] op_sel:[0,1,0]
	v_pk_fma_f32 v[30:31], v[128:129], v[38:39], v[30:31] op_sel:[0,1,0]
	v_pk_fma_f32 v[148:149], v[130:131], v[2:3], v[0:1] op_sel_hi:[1,0,1]
	s_waitcnt lgkmcnt(3)
	v_pk_fma_f32 v[0:1], v[126:127], v[14:15], v[88:89] op_sel_hi:[1,0,1]
	v_pk_fma_f32 v[146:147], v[130:131], v[40:41], v[30:31] op_sel_hi:[1,0,1]
	ds_read_b128 v[30:33], v67
	v_pk_fma_f32 v[0:1], v[128:129], v[14:15], v[0:1] op_sel:[0,1,0]
	v_mov_b32_e32 v144, v37
	ds_read_b128 v[34:37], v71
	v_pk_fma_f32 v[0:1], v[130:131], v[16:17], v[0:1] op_sel_hi:[1,0,1]
	v_mov_b32_e32 v14, v17
	s_waitcnt lgkmcnt(4)
	v_pk_fma_f32 v[16:17], v[126:127], v[18:19], v[108:109] op_sel_hi:[1,0,1]
	s_add_i32 s26, s3, 0xfffef000
	v_mov_b32_e32 v142, v41
	v_pk_fma_f32 v[16:17], v[128:129], v[18:19], v[16:17] op_sel:[0,1,0]
	ds_read_b128 v[38:41], v44
	s_waitcnt lgkmcnt(4)
	v_pk_fma_f32 v[18:19], v[126:127], v[22:23], v[176:177] op_sel_hi:[1,0,1]
	v_mov_b32_e32 v46, s26
	v_pk_fma_f32 v[18:19], v[128:129], v[22:23], v[18:19] op_sel:[0,1,0]
	s_waitcnt lgkmcnt(3)
	v_pk_fma_f32 v[22:23], v[126:127], v[26:27], v[180:181] op_sel_hi:[1,0,1]
	ds_read_b128 v[46:49], v46
	ds_read_b128 v[42:45], v75
	ds_read_b128 v[50:53], v95
	v_pk_fma_f32 v[22:23], v[128:129], v[26:27], v[22:23] op_sel:[0,1,0]
	v_mov_b32_e32 v26, v29
	v_pk_fma_f32 v[22:23], v[130:131], v[28:29], v[22:23] op_sel_hi:[1,0,1]
	s_waitcnt lgkmcnt(5)
	v_pk_fma_f32 v[28:29], v[126:127], v[30:31], v[182:183] op_sel_hi:[1,0,1]
	ds_read_b128 v[54:57], v99
	ds_read_b128 v[58:61], v119
	v_pk_fma_f32 v[28:29], v[128:129], v[30:31], v[28:29] op_sel:[0,1,0]
	s_waitcnt lgkmcnt(6)
	v_pk_fma_f32 v[30:31], v[126:127], v[34:35], v[184:185] op_sel_hi:[1,0,1]
	s_add_i32 s31, s3, 0xffff4000
	v_pk_fma_f32 v[30:31], v[128:129], v[34:35], v[30:31] op_sel:[0,1,0]
	s_waitcnt lgkmcnt(5)
	v_pk_fma_f32 v[34:35], v[126:127], v[38:39], v[186:187] op_sel_hi:[1,0,1]
	v_mov_b32_e32 v133, s31
	v_pk_fma_f32 v[34:35], v[128:129], v[38:39], v[34:35] op_sel:[0,1,0]
	v_mov_b32_e32 v38, v41
	v_pk_fma_f32 v[34:35], v[130:131], v[40:41], v[34:35] op_sel_hi:[1,0,1]
	s_waitcnt lgkmcnt(3)
	v_pk_fma_f32 v[40:41], v[126:127], v[42:43], v[188:189] op_sel_hi:[1,0,1]
	ds_read_b128 v[62:65], v123
	ds_read_b128 v[66:69], v133
	v_pk_fma_f32 v[40:41], v[128:129], v[42:43], v[40:41] op_sel:[0,1,0]
	v_pk_fma_f32 v[42:43], v[126:127], v[46:47], v[190:191] op_sel_hi:[1,0,1]
	v_mov_b32_e32 v150, v3
	v_pk_fma_f32 v[42:43], v[128:129], v[46:47], v[42:43] op_sel:[0,1,0]
	s_waitcnt lgkmcnt(4)
	v_pk_fma_f32 v[46:47], v[126:127], v[50:51], v[192:193] op_sel_hi:[1,0,1]
	v_mov_b32_e32 v3, s33
	v_pk_fma_f32 v[46:47], v[128:129], v[50:51], v[46:47] op_sel:[0,1,0]
	v_mov_b32_e32 v50, v53
	v_pk_fma_f32 v[46:47], v[130:131], v[52:53], v[46:47] op_sel_hi:[1,0,1]
	s_waitcnt lgkmcnt(3)
	v_pk_fma_f32 v[52:53], v[126:127], v[54:55], v[194:195] op_sel_hi:[1,0,1]
	v_mov_b32_e32 v15, s34
	v_pk_fma_f32 v[52:53], v[128:129], v[54:55], v[52:53] op_sel:[0,1,0]
	s_waitcnt lgkmcnt(2)
	v_pk_fma_f32 v[54:55], v[126:127], v[58:59], v[196:197] op_sel_hi:[1,0,1]
	s_add_i32 s6, s3, 0xffff7000
	v_pk_fma_f32 v[54:55], v[128:129], v[58:59], v[54:55] op_sel:[0,1,0]
	s_waitcnt lgkmcnt(1)
	v_pk_fma_f32 v[58:59], v[126:127], v[62:63], v[198:199] op_sel_hi:[1,0,1]
	s_add_i32 s7, s3, 0xffff8000
	v_pk_fma_f32 v[58:59], v[128:129], v[62:63], v[58:59] op_sel:[0,1,0]
	s_waitcnt lgkmcnt(0)
	v_pk_fma_f32 v[62:63], v[126:127], v[66:67], v[200:201] op_sel_hi:[1,0,1]
	v_pk_fma_f32 v[58:59], v[130:131], v[64:65], v[58:59] op_sel_hi:[1,0,1]
	v_pk_fma_f32 v[62:63], v[128:129], v[66:67], v[62:63] op_sel:[0,1,0]
	v_mov_b32_e32 v64, v69
	v_pk_fma_f32 v[62:63], v[130:131], v[68:69], v[62:63] op_sel_hi:[1,0,1]
	ds_read_b128 v[66:69], v3
	ds_read_b128 v[70:73], v15
	v_mov_b32_e32 v3, s6
	v_mov_b32_e32 v15, s7
	ds_read_b128 v[90:93], v3
	ds_read_b128 v[94:97], v15
	s_waitcnt lgkmcnt(3)
	v_pk_fma_f32 v[88:89], v[126:127], v[66:67], v[202:203] op_sel_hi:[1,0,1]
	s_add_i32 s6, s3, 0xffff9000
	v_pk_fma_f32 v[66:67], v[128:129], v[66:67], v[88:89] op_sel:[0,1,0]
	s_waitcnt lgkmcnt(2)
; #define LAS __attribute__((address_space(3)))
; __device__ __forceinline__ void phase0(CArgs a, LAS unsigned char* lds, int tid, int lane, int wave, int G, int bx) {
;     ...
;             for (int kk = 0; kk < 128; kk += 16) {
;                 const int k = kb + kk; const float* wp = Wl + (size_t)(half * 1024 + k) * NMOD;
;                 f32x2 wv[16];
; #pragma unroll
;                 for (int i = 0; i < 16; ++i) wv[i] = __builtin_nontemporal_load((const f32x2*)(wp + (size_t)i * NMOD));
; #pragma unroll
;                 for (int q = 0; q < 4; ++q) {
; #pragma unroll
;                     for (int r = 0; r < NB; ++r) { const f32x4 s4 = *(const LAS f32x4*)(S + r * 1024 + k + 4 * q);
;                         acc[r] += wv[4 * q] * s4[0]; acc[r] += wv[4 * q + 1] * s4[1]; acc[r] += wv[4 * q + 2] * s4[2]; acc[r] += wv[4 * q + 3] * s4[3]; } }
	v_pk_fma_f32 v[88:89], v[126:127], v[70:71], v[204:205] op_sel_hi:[1,0,1]
	s_add_i32 s7, s3, 0xffffa000
	v_mov_b32_e32 v3, s6
	v_pk_fma_f32 v[70:71], v[128:129], v[70:71], v[88:89] op_sel:[0,1,0]
	s_waitcnt lgkmcnt(1)
	v_pk_fma_f32 v[88:89], v[126:127], v[90:91], v[174:175] op_sel_hi:[1,0,1]
	v_mov_b32_e32 v15, s7
	ds_read_b128 v[98:101], v3
	ds_read_b128 v[102:105], v15
	v_pk_fma_f32 v[88:89], v[128:129], v[90:91], v[88:89] op_sel:[0,1,0]
	s_add_i32 s6, s3, 0xffffb000
	v_pk_fma_f32 v[90:91], v[130:131], v[92:93], v[88:89] op_sel_hi:[1,0,1]
	s_waitcnt lgkmcnt(2)
	v_pk_fma_f32 v[88:89], v[126:127], v[94:95], v[172:173] op_sel_hi:[1,0,1]
	s_add_i32 s7, s3, 0xffffc000
	v_pk_fma_f32 v[88:89], v[128:129], v[94:95], v[88:89] op_sel:[0,1,0]
	v_mov_b32_e32 v3, s6
	v_pk_fma_f32 v[94:95], v[130:131], v[96:97], v[88:89] op_sel_hi:[1,0,1]
	s_waitcnt lgkmcnt(1)
	v_pk_fma_f32 v[88:89], v[126:127], v[98:99], v[170:171] op_sel_hi:[1,0,1]
	v_mov_b32_e32 v15, s7
	ds_read_b128 v[106:109], v3
	ds_read_b128 v[110:113], v15
	v_pk_fma_f32 v[88:89], v[128:129], v[98:99], v[88:89] op_sel:[0,1,0]
	s_add_i32 s6, s3, 0xffffd000
	v_pk_fma_f32 v[98:99], v[130:131], v[100:101], v[88:89] op_sel_hi:[1,0,1]
	s_waitcnt lgkmcnt(2)
	v_pk_fma_f32 v[88:89], v[126:127], v[102:103], v[168:169] op_sel_hi:[1,0,1]
	s_add_i32 s7, s3, 0xffffe000
	v_pk_fma_f32 v[88:89], v[128:129], v[102:103], v[88:89] op_sel:[0,1,0]
	v_mov_b32_e32 v3, s6
	v_pk_fma_f32 v[102:103], v[130:131], v[104:105], v[88:89] op_sel_hi:[1,0,1]
	s_waitcnt lgkmcnt(1)
	v_pk_fma_f32 v[88:89], v[126:127], v[106:107], v[158:159] op_sel_hi:[1,0,1]
	v_mov_b32_e32 v15, s7
	ds_read_b128 v[114:117], v3
	ds_read_b128 v[118:121], v15
	v_pk_fma_f32 v[88:89], v[128:129], v[106:107], v[88:89] op_sel:[0,1,0]
	s_add_i32 s6, s3, 0xfffff000
	v_pk_fma_f32 v[106:107], v[130:131], v[108:109], v[88:89] op_sel_hi:[1,0,1]
	s_waitcnt lgkmcnt(2)
	v_pk_fma_f32 v[88:89], v[126:127], v[110:111], v[156:157] op_sel_hi:[1,0,1]
	v_mov_b32_e32 v15, s6
	v_pk_fma_f32 v[88:89], v[128:129], v[110:111], v[88:89] op_sel:[0,1,0]
	v_mov_b32_e32 v3, s3
	v_pk_fma_f32 v[110:111], v[130:131], v[112:113], v[88:89] op_sel_hi:[1,0,1]
	s_waitcnt lgkmcnt(1)
	v_pk_fma_f32 v[88:89], v[126:127], v[114:115], v[154:155] op_sel_hi:[1,0,1]
	v_pk_fma_f32 v[16:17], v[130:131], v[20:21], v[16:17] op_sel_hi:[1,0,1]
	v_pk_fma_f32 v[88:89], v[128:129], v[114:115], v[88:89] op_sel:[0,1,0]
	v_pk_fma_f32 v[18:19], v[130:131], v[24:25], v[18:19] op_sel_hi:[1,0,1]
	v_pk_fma_f32 v[114:115], v[130:131], v[116:117], v[88:89] op_sel_hi:[1,0,1]
	s_waitcnt lgkmcnt(0)
	v_pk_fma_f32 v[88:89], v[126:127], v[118:119], v[152:153] op_sel_hi:[1,0,1]
	ds_read_b128 v[152:155], v15
	ds_read_b128 v[156:159], v3
	v_pk_fma_f32 v[88:89], v[128:129], v[118:119], v[88:89] op_sel:[0,1,0]
	v_pk_fma_f32 v[28:29], v[130:131], v[32:33], v[28:29] op_sel_hi:[1,0,1]
	v_pk_fma_f32 v[118:119], v[130:131], v[120:121], v[88:89] op_sel_hi:[1,0,1]
	s_waitcnt lgkmcnt(1)
	v_pk_fma_f32 v[88:89], v[126:127], v[152:153], v[124:125] op_sel_hi:[1,0,1]
	s_waitcnt lgkmcnt(0)
	v_pk_fma_f32 v[86:87], v[126:127], v[156:157], v[86:87] op_sel_hi:[1,0,1]
	v_pk_fma_f32 v[88:89], v[128:129], v[152:153], v[88:89] op_sel:[0,1,0]
	v_pk_fma_f32 v[86:87], v[128:129], v[156:157], v[86:87] op_sel:[0,1,0]
	v_pk_fma_f32 v[30:31], v[130:131], v[36:37], v[30:31] op_sel_hi:[1,0,1]
	v_pk_fma_f32 v[40:41], v[130:131], v[44:45], v[40:41] op_sel_hi:[1,0,1]
	v_pk_fma_f32 v[42:43], v[130:131], v[48:49], v[42:43] op_sel_hi:[1,0,1]
	v_pk_fma_f32 v[52:53], v[130:131], v[56:57], v[52:53] op_sel_hi:[1,0,1]
	v_pk_fma_f32 v[54:55], v[130:131], v[60:61], v[54:55] op_sel_hi:[1,0,1]
	v_pk_fma_f32 v[66:67], v[130:131], v[68:69], v[66:67] op_sel_hi:[1,0,1]
	v_pk_fma_f32 v[70:71], v[130:131], v[72:73], v[70:71] op_sel_hi:[1,0,1]
	v_pk_fma_f32 v[122:123], v[130:131], v[154:155], v[88:89] op_sel_hi:[1,0,1]
	v_pk_fma_f32 v[126:127], v[130:131], v[158:159], v[86:87] op_sel_hi:[1,0,1]
	v_mov_b32_e32 v2, v21
	v_mov_b32_e32 v20, v25
	v_mov_b32_e32 v24, v33
	v_mov_b32_e32 v32, v37
	v_mov_b32_e32 v36, v45
	v_mov_b32_e32 v44, v49
	v_mov_b32_e32 v48, v57
	v_mov_b32_e32 v56, v61
	v_mov_b32_e32 v60, v65
	v_mov_b32_e32 v68, v69
	v_mov_b32_e32 v72, v73
	v_mov_b32_e32 v92, v93
	v_mov_b32_e32 v96, v97
	v_mov_b32_e32 v100, v101
	v_mov_b32_e32 v104, v105
	v_mov_b32_e32 v108, v109
	v_mov_b32_e32 v112, v113
	v_mov_b32_e32 v116, v117
	v_mov_b32_e32 v120, v121
	v_mov_b32_e32 v124, v155
	v_mov_b32_e32 v128, v159
	s_add_i32 s3, s3, 64
	s_mov_b64 s[6:7], 0xc0000
	v_lshl_add_u64 v[12:13], v[12:13], 0, s[6:7]
	s_cmpk_gt_u32 s2, 0x6f
	s_waitcnt vmcnt(15)
; #define LAS __attribute__((address_space(3)))
; __device__ __forceinline__ void phase0(CArgs a, LAS unsigned char* lds, int tid, int lane, int wave, int G, int bx) {
;     ...
;                 for (int i = 0; i < 16; ++i) wv[i] = __builtin_nontemporal_load((const f32x2*)(wp + (size_t)i * NMOD));
; #pragma unroll
;                 for (int q = 0; q < 4; ++q) {
; #pragma unroll
;                     for (int r = 0; r < NB; ++r) { const f32x4 s4 = *(const LAS f32x4*)(S + r * 1024 + k + 4 * q);
;                         acc[r] += wv[4 * q] * s4[0]; acc[r] += wv[4 * q + 1] * s4[1]; acc[r] += wv[4 * q + 2] * s4[2]; acc[r] += wv[4 * q + 3] * s4[3]; } }
;             }
;         }
;         __syncthreads();
; #pragma unroll
;         for (int r = 0; r < NB; ++r) *(LAS f32x2*)(S + (wave * NB + r) * 128 + lane * 2) = acc[r];
;         __syncthreads();
;         float* MOD = (float*)(ws + WS_MOD);
;         for (int idx = tid; idx < NB * 128; idx += 512) { const int r = idx >> 7, col = idx & 127; float s = a->in[11][l * NMOD + cb * 128 + col];
; #pragma unroll
;             for (int w = 0; w < 8; ++w) s += S[(w * NB + r) * 128 + col];
;             MOD[(size_t)(l * NB + r) * NMOD + cb * 128 + col] = s; }
	v_mov_b32_e32 v130, v250
	v_mov_b32_e32 v131, v251
	global_load_dwordx2 v[250:251], v[208:209], off nt
	v_pk_fma_f32 v[88:89], v[130:131], v[74:75], v[76:77] op_sel_hi:[1,0,1]
	v_pk_fma_f32 v[86:87], v[130:131], v[80:81], v[78:79] op_sel_hi:[1,0,1]
	v_pk_fma_f32 v[84:85], v[130:131], v[84:85], v[82:83] op_sel_hi:[1,0,1]
	v_pk_fma_f32 v[82:83], v[130:131], v[132:133], v[134:135] op_sel_hi:[1,0,1]
	v_pk_fma_f32 v[80:81], v[130:131], v[138:139], v[136:137] op_sel_hi:[1,0,1]
	v_pk_fma_f32 v[78:79], v[130:131], v[144:145], v[140:141] op_sel_hi:[1,0,1]
	v_pk_fma_f32 v[76:77], v[130:131], v[142:143], v[146:147] op_sel_hi:[1,0,1]
	v_pk_fma_f32 v[74:75], v[130:131], v[150:151], v[148:149] op_sel_hi:[1,0,1]
	v_pk_fma_f32 v[152:153], v[130:131], v[14:15], v[0:1] op_sel_hi:[1,0,1]
	v_pk_fma_f32 v[150:151], v[130:131], v[2:3], v[16:17] op_sel_hi:[1,0,1]
	v_pk_fma_f32 v[148:149], v[130:131], v[20:21], v[18:19] op_sel_hi:[1,0,1]
	v_pk_fma_f32 v[146:147], v[130:131], v[26:27], v[22:23] op_sel_hi:[1,0,1]
	v_pk_fma_f32 v[144:145], v[130:131], v[24:25], v[28:29] op_sel_hi:[1,0,1]
	v_pk_fma_f32 v[142:143], v[130:131], v[32:33], v[30:31] op_sel_hi:[1,0,1]
	v_pk_fma_f32 v[140:141], v[130:131], v[38:39], v[34:35] op_sel_hi:[1,0,1]
	v_pk_fma_f32 v[134:135], v[130:131], v[36:37], v[40:41] op_sel_hi:[1,0,1]
	v_pk_fma_f32 v[2:3], v[130:131], v[44:45], v[42:43] op_sel_hi:[1,0,1]
	v_pk_fma_f32 v[0:1], v[130:131], v[50:51], v[46:47] op_sel_hi:[1,0,1]
	v_pk_fma_f32 v[138:139], v[130:131], v[48:49], v[52:53] op_sel_hi:[1,0,1]
	v_pk_fma_f32 v[136:137], v[130:131], v[56:57], v[54:55] op_sel_hi:[1,0,1]
	v_pk_fma_f32 v[132:133], v[130:131], v[60:61], v[58:59] op_sel_hi:[1,0,1]
	v_pk_fma_f32 v[40:41], v[130:131], v[64:65], v[62:63] op_sel_hi:[1,0,1]
	v_pk_fma_f32 v[38:39], v[130:131], v[68:69], v[66:67] op_sel_hi:[1,0,1]
	v_pk_fma_f32 v[36:37], v[130:131], v[72:73], v[70:71] op_sel_hi:[1,0,1]
	v_pk_fma_f32 v[32:33], v[130:131], v[92:93], v[90:91] op_sel_hi:[1,0,1]
	v_pk_fma_f32 v[30:31], v[130:131], v[96:97], v[94:95] op_sel_hi:[1,0,1]
	v_pk_fma_f32 v[28:29], v[130:131], v[100:101], v[98:99] op_sel_hi:[1,0,1]
	v_pk_fma_f32 v[26:27], v[130:131], v[104:105], v[102:103] op_sel_hi:[1,0,1]
	v_pk_fma_f32 v[24:25], v[130:131], v[108:109], v[106:107] op_sel_hi:[1,0,1]
	v_pk_fma_f32 v[22:23], v[130:131], v[112:113], v[110:111] op_sel_hi:[1,0,1]
	v_pk_fma_f32 v[20:21], v[130:131], v[116:117], v[114:115] op_sel_hi:[1,0,1]
	v_pk_fma_f32 v[18:19], v[130:131], v[120:121], v[118:119] op_sel_hi:[1,0,1]
	v_pk_fma_f32 v[16:17], v[130:131], v[124:125], v[122:123] op_sel_hi:[1,0,1]
	v_pk_fma_f32 v[14:15], v[130:131], v[128:129], v[126:127] op_sel_hi:[1,0,1]
	s_cbranch_scc0 .LBB0_843
	s_waitcnt vmcnt(0)
	s_movk_i32 s14, 0x400
	s_mov_b64 s[6:7], 0
	s_and_b64 vcc, exec, s[4:5]
	s_cbranch_vccz .LBB0_835
	s_barrier
	ds_write2st64_b64 v5, v[88:89], v[86:87] offset1:1
	ds_write2st64_b64 v5, v[84:85], v[82:83] offset0:2 offset1:3
	ds_write2st64_b64 v5, v[80:81], v[78:79] offset0:4 offset1:5
	ds_write2st64_b64 v5, v[76:77], v[74:75] offset0:6 offset1:7
	ds_write2st64_b64 v5, v[152:153], v[150:151] offset0:8 offset1:9
	ds_write2st64_b64 v5, v[148:149], v[146:147] offset0:10 offset1:11
	ds_write2st64_b64 v5, v[144:145], v[142:143] offset0:12 offset1:13
	ds_write2st64_b64 v5, v[140:141], v[134:135] offset0:14 offset1:15
	ds_write2st64_b64 v5, v[2:3], v[0:1] offset0:16 offset1:17
	ds_write2st64_b64 v5, v[138:139], v[136:137] offset0:18 offset1:19
	ds_write2st64_b64 v5, v[132:133], v[40:41] offset0:20 offset1:21
	ds_write2st64_b64 v5, v[38:39], v[36:37] offset0:22 offset1:23
	ds_write2st64_b64 v5, v[32:33], v[30:31] offset0:24 offset1:25
	ds_write2st64_b64 v5, v[28:29], v[26:27] offset0:26 offset1:27
	ds_write2st64_b64 v5, v[24:25], v[22:23] offset0:28 offset1:29
	ds_write2st64_b64 v5, v[20:21], v[18:19] offset0:30 offset1:31
	ds_write2st64_b64 v5, v[16:17], v[14:15] offset0:32 offset1:33
	s_waitcnt lgkmcnt(0)
	s_barrier
	s_and_saveexec_b64 s[4:5], s[40:41]
	v_readlane_b32 s28, v254, 20
	s_mov_b64 s[30:31], 0x800
	v_readlane_b32 s29, v254, 21
	s_cbranch_execz .LBB0_833
	s_load_dwordx2 s[2:3], s[92:93], 0x58
	s_mul_i32 s6, s13, 0x3000
	s_add_i32 s6, s6, s0
	v_or_b32_e32 v0, s6, v165
	v_ashrrev_i32_e32 v1, 31, v0
	s_mul_i32 s13, s13, 34
	s_waitcnt lgkmcnt(0)
	v_lshl_add_u64 v[0:1], v[0:1], 2, s[2:3]
	v_lshl_add_u64 v[2:3], s[0:1], 2, v[6:7]
	s_mov_b64 s[0:1], 0
	v_mov_b32_e32 v10, v164
